# v25 plus the twenty duplicate s_waitcnt lgkmcnt(0) at the head of the GEMM MFMA blocks removed (the identical wait sits just above the barrier, nothing is issued in between)
# speedup vs baseline: 1.0336x; 1.0038x over previous
.LBB0_131:
	ds_read_b128 v[152:155], v145
	ds_read_b128 v[156:159], v145 offset:1024
	ds_read_b128 v[160:163], v145 offset:2048
	ds_read_b128 v[168:171], v145 offset:3072
	ds_read_b128 v[172:175], v146
	ds_read_b128 v[176:179], v146 offset:1024
	ds_read_b128 v[180:183], v146 offset:2048
	ds_read_b128 v[184:187], v146 offset:3072
	s_add_i32 s26, s24, 0xfdfc0080
	s_cmp_lg_u32 s34, 12
	s_cselect_b32 s26, s26, 0
	s_add_u32 s36, s8, s26
	s_addc_u32 s37, s9, 0
	s_add_u32 s26, s6, s26
	s_addc_u32 s27, s7, 0
	s_mov_b32 m0, s35
	v_lshl_add_u64 v[220:221], v[140:141], 0, s[24:25]
	ds_read_b128 v[188:191], v147
	ds_read_b128 v[192:195], v147 offset:1024
	ds_read_b128 v[196:199], v147 offset:2048
	ds_read_b128 v[200:203], v147 offset:3072
	ds_read_b128 v[204:207], v147 offset:4096
	ds_read_b128 v[208:211], v147 offset:5120
	ds_read_b128 v[212:215], v147 offset:6144
	ds_read_b128 v[216:219], v147 offset:7168
	global_load_lds_dwordx4 v[220:221], off
	v_lshl_add_u64 v[220:221], v[142:143], 0, s[24:25]
	s_mov_b32 m0, s38
	s_nop 0
	global_load_lds_dwordx4 v[220:221], off
	s_waitcnt vmcnt(8)
	s_waitcnt lgkmcnt(0)
	s_barrier
	s_setprio 1
	v_mfma_f32_16x16x32_bf16 v[124:127], v[152:155], v[188:191], v[124:127]
	v_mfma_f32_16x16x32_bf16 v[120:123], v[160:163], v[188:191], v[120:123]
	v_mfma_f32_16x16x32_bf16 v[108:111], v[152:155], v[196:199], v[108:111]
	v_mfma_f32_16x16x32_bf16 v[104:107], v[160:163], v[196:199], v[104:107]
	v_mfma_f32_16x16x32_bf16 v[92:95], v[152:155], v[204:207], v[92:95]
	v_mfma_f32_16x16x32_bf16 v[88:91], v[160:163], v[204:207], v[88:91]
	v_mfma_f32_16x16x32_bf16 v[76:79], v[152:155], v[212:215], v[76:79]
	v_mfma_f32_16x16x32_bf16 v[72:75], v[160:163], v[212:215], v[72:75]
	v_mfma_f32_16x16x32_bf16 v[124:127], v[156:159], v[192:195], v[124:127]
	v_mfma_f32_16x16x32_bf16 v[120:123], v[168:171], v[192:195], v[120:123]
	v_mfma_f32_16x16x32_bf16 v[108:111], v[156:159], v[200:203], v[108:111]
	v_mfma_f32_16x16x32_bf16 v[104:107], v[168:171], v[200:203], v[104:107]
	v_mfma_f32_16x16x32_bf16 v[92:95], v[156:159], v[208:211], v[92:95]
	v_mfma_f32_16x16x32_bf16 v[88:91], v[168:171], v[208:211], v[88:91]
	v_mfma_f32_16x16x32_bf16 v[76:79], v[156:159], v[216:219], v[76:79]
	v_mfma_f32_16x16x32_bf16 v[72:75], v[168:171], v[216:219], v[72:75]
	v_mfma_f32_16x16x32_bf16 v[116:119], v[172:175], v[188:191], v[116:119]
	v_mfma_f32_16x16x32_bf16 v[112:115], v[180:183], v[188:191], v[112:115]
	v_mfma_f32_16x16x32_bf16 v[100:103], v[172:175], v[196:199], v[100:103]
	v_mfma_f32_16x16x32_bf16 v[96:99], v[180:183], v[196:199], v[96:99]
	v_mfma_f32_16x16x32_bf16 v[84:87], v[172:175], v[204:207], v[84:87]
	v_mfma_f32_16x16x32_bf16 v[80:83], v[180:183], v[204:207], v[80:83]
	v_mfma_f32_16x16x32_bf16 v[68:71], v[172:175], v[212:215], v[68:71]
	v_mfma_f32_16x16x32_bf16 v[64:67], v[180:183], v[212:215], v[64:67]
	v_mfma_f32_16x16x32_bf16 v[116:119], v[176:179], v[192:195], v[116:119]
	v_mfma_f32_16x16x32_bf16 v[112:115], v[184:187], v[192:195], v[112:115]
	v_mfma_f32_16x16x32_bf16 v[100:103], v[176:179], v[200:203], v[100:103]
	v_mfma_f32_16x16x32_bf16 v[96:99], v[184:187], v[200:203], v[96:99]
	v_mfma_f32_16x16x32_bf16 v[84:87], v[176:179], v[208:211], v[84:87]
	v_mfma_f32_16x16x32_bf16 v[80:83], v[184:187], v[208:211], v[80:83]
	v_mfma_f32_16x16x32_bf16 v[68:71], v[176:179], v[216:219], v[68:71]
	v_mfma_f32_16x16x32_bf16 v[64:67], v[184:187], v[216:219], v[64:67]
	s_setprio 0
	s_barrier
	s_mov_b32 m0, s39
	v_lshl_add_u64 v[220:221], s[26:27], 0, v[130:131]
	s_add_u32 s48, s26, 0x40000
	ds_read_b128 v[188:191], v147 offset:16384
	ds_read_b128 v[192:195], v147 offset:17408
	ds_read_b128 v[196:199], v147 offset:18432
	ds_read_b128 v[200:203], v147 offset:19456
	ds_read_b128 v[204:207], v147 offset:20480
	ds_read_b128 v[208:211], v147 offset:21504
	ds_read_b128 v[212:215], v147 offset:22528
	ds_read_b128 v[216:219], v147 offset:23552
	global_load_lds_dwordx4 v[220:221], off
	v_lshl_add_u64 v[222:223], s[26:27], 0, v[134:135]
	s_mov_b32 m0, s41
	s_addc_u32 s49, s27, 0
	global_load_lds_dwordx4 v[222:223], off
	v_lshl_add_u64 v[224:225], s[48:49], 0, v[130:131]
	s_mov_b32 m0, s42
	v_lshl_add_u64 v[226:227], s[36:37], 0, v[132:133]
	global_load_lds_dwordx4 v[224:225], off
	v_lshl_add_u64 v[224:225], s[48:49], 0, v[134:135]
	s_mov_b32 m0, s43
	s_nop 0
	global_load_lds_dwordx4 v[224:225], off
	v_lshl_add_u64 v[224:225], s[36:37], 0, v[128:129]
	s_mov_b32 m0, s3
	s_nop 0
	global_load_lds_dwordx4 v[224:225], off
	s_mov_b32 m0, s5
	s_nop 0
	global_load_lds_dwordx4 v[226:227], off
	s_waitcnt vmcnt(8)
	s_waitcnt lgkmcnt(0)
	s_barrier
	s_setprio 1
	v_mfma_f32_16x16x32_bf16 v[60:63], v[152:155], v[188:191], v[60:63]
	v_mfma_f32_16x16x32_bf16 v[56:59], v[160:163], v[188:191], v[56:59]
	v_mfma_f32_16x16x32_bf16 v[44:47], v[152:155], v[196:199], v[44:47]
	v_mfma_f32_16x16x32_bf16 v[40:43], v[160:163], v[196:199], v[40:43]
	v_mfma_f32_16x16x32_bf16 v[28:31], v[152:155], v[204:207], v[28:31]
	v_mfma_f32_16x16x32_bf16 v[24:27], v[160:163], v[204:207], v[24:27]
	v_mfma_f32_16x16x32_bf16 v[12:15], v[152:155], v[212:215], v[12:15]
	v_mfma_f32_16x16x32_bf16 v[8:11], v[160:163], v[212:215], v[8:11]
	v_mfma_f32_16x16x32_bf16 v[60:63], v[156:159], v[192:195], v[60:63]
	v_mfma_f32_16x16x32_bf16 v[56:59], v[168:171], v[192:195], v[56:59]
	v_mfma_f32_16x16x32_bf16 v[44:47], v[156:159], v[200:203], v[44:47]
	v_mfma_f32_16x16x32_bf16 v[40:43], v[168:171], v[200:203], v[40:43]
	v_mfma_f32_16x16x32_bf16 v[28:31], v[156:159], v[208:211], v[28:31]
	v_mfma_f32_16x16x32_bf16 v[24:27], v[168:171], v[208:211], v[24:27]
	v_mfma_f32_16x16x32_bf16 v[12:15], v[156:159], v[216:219], v[12:15]
	v_mfma_f32_16x16x32_bf16 v[8:11], v[168:171], v[216:219], v[8:11]
	v_mfma_f32_16x16x32_bf16 v[52:55], v[172:175], v[188:191], v[52:55]
	v_mfma_f32_16x16x32_bf16 v[48:51], v[180:183], v[188:191], v[48:51]
	v_mfma_f32_16x16x32_bf16 v[36:39], v[172:175], v[196:199], v[36:39]
	v_mfma_f32_16x16x32_bf16 v[32:35], v[180:183], v[196:199], v[32:35]
	v_mfma_f32_16x16x32_bf16 v[20:23], v[172:175], v[204:207], v[20:23]
	v_mfma_f32_16x16x32_bf16 v[16:19], v[180:183], v[204:207], v[16:19]
	v_mfma_f32_16x16x32_bf16 v[4:7], v[172:175], v[212:215], v[4:7]
	v_mfma_f32_16x16x32_bf16 v[0:3], v[180:183], v[212:215], v[0:3]
	v_mfma_f32_16x16x32_bf16 v[52:55], v[176:179], v[192:195], v[52:55]
	v_mfma_f32_16x16x32_bf16 v[48:51], v[184:187], v[192:195], v[48:51]
	v_mfma_f32_16x16x32_bf16 v[36:39], v[176:179], v[200:203], v[36:39]
	v_mfma_f32_16x16x32_bf16 v[32:35], v[184:187], v[200:203], v[32:35]
	v_mfma_f32_16x16x32_bf16 v[20:23], v[176:179], v[208:211], v[20:23]
	v_mfma_f32_16x16x32_bf16 v[16:19], v[184:187], v[208:211], v[16:19]
	v_mfma_f32_16x16x32_bf16 v[4:7], v[176:179], v[216:219], v[4:7]
	v_mfma_f32_16x16x32_bf16 v[0:3], v[184:187], v[216:219], v[0:3]
	s_setprio 0
	s_barrier
	ds_read_b128 v[152:155], v148
	ds_read_b128 v[156:159], v148 offset:1024
	ds_read_b128 v[160:163], v148 offset:2048
	ds_read_b128 v[168:171], v148 offset:3072
	ds_read_b128 v[172:175], v150
	ds_read_b128 v[176:179], v150 offset:1024
	ds_read_b128 v[180:183], v150 offset:2048
	ds_read_b128 v[184:187], v150 offset:3072
	s_add_u32 s36, s36, 0x40000
	s_addc_u32 s37, s37, 0
	s_mov_b32 m0, s13
	v_lshl_add_u64 v[228:229], s[36:37], 0, v[128:129]
	ds_read_b128 v[188:191], v147 offset:32768
	ds_read_b128 v[192:195], v147 offset:33792
	ds_read_b128 v[196:199], v147 offset:34816
	ds_read_b128 v[200:203], v147 offset:35840
	ds_read_b128 v[204:207], v147 offset:36864
	ds_read_b128 v[208:211], v147 offset:37888
	ds_read_b128 v[212:215], v147 offset:38912
	ds_read_b128 v[216:219], v147 offset:39936
	global_load_lds_dwordx4 v[228:229], off
	v_lshl_add_u64 v[228:229], s[36:37], 0, v[132:133]
	s_mov_b32 m0, s15
	s_nop 0
	global_load_lds_dwordx4 v[228:229], off
	s_waitcnt vmcnt(8)
	s_waitcnt lgkmcnt(0)
	s_barrier
	s_setprio 1
	v_mfma_f32_16x16x32_bf16 v[124:127], v[152:155], v[188:191], v[124:127]
	v_mfma_f32_16x16x32_bf16 v[120:123], v[160:163], v[188:191], v[120:123]
	v_mfma_f32_16x16x32_bf16 v[108:111], v[152:155], v[196:199], v[108:111]
	v_mfma_f32_16x16x32_bf16 v[104:107], v[160:163], v[196:199], v[104:107]
	v_mfma_f32_16x16x32_bf16 v[92:95], v[152:155], v[204:207], v[92:95]
	v_mfma_f32_16x16x32_bf16 v[88:91], v[160:163], v[204:207], v[88:91]
	v_mfma_f32_16x16x32_bf16 v[76:79], v[152:155], v[212:215], v[76:79]
	v_mfma_f32_16x16x32_bf16 v[72:75], v[160:163], v[212:215], v[72:75]
	v_mfma_f32_16x16x32_bf16 v[124:127], v[156:159], v[192:195], v[124:127]
	v_mfma_f32_16x16x32_bf16 v[120:123], v[168:171], v[192:195], v[120:123]
	v_mfma_f32_16x16x32_bf16 v[108:111], v[156:159], v[200:203], v[108:111]
	v_mfma_f32_16x16x32_bf16 v[104:107], v[168:171], v[200:203], v[104:107]
	v_mfma_f32_16x16x32_bf16 v[92:95], v[156:159], v[208:211], v[92:95]
	v_mfma_f32_16x16x32_bf16 v[88:91], v[168:171], v[208:211], v[88:91]
	v_mfma_f32_16x16x32_bf16 v[76:79], v[156:159], v[216:219], v[76:79]
	v_mfma_f32_16x16x32_bf16 v[72:75], v[168:171], v[216:219], v[72:75]
	v_mfma_f32_16x16x32_bf16 v[116:119], v[172:175], v[188:191], v[116:119]
	v_mfma_f32_16x16x32_bf16 v[112:115], v[180:183], v[188:191], v[112:115]
	v_mfma_f32_16x16x32_bf16 v[100:103], v[172:175], v[196:199], v[100:103]
	v_mfma_f32_16x16x32_bf16 v[96:99], v[180:183], v[196:199], v[96:99]
	v_mfma_f32_16x16x32_bf16 v[84:87], v[172:175], v[204:207], v[84:87]
	v_mfma_f32_16x16x32_bf16 v[80:83], v[180:183], v[204:207], v[80:83]
	v_mfma_f32_16x16x32_bf16 v[68:71], v[172:175], v[212:215], v[68:71]
	v_mfma_f32_16x16x32_bf16 v[64:67], v[180:183], v[212:215], v[64:67]
	v_mfma_f32_16x16x32_bf16 v[116:119], v[176:179], v[192:195], v[116:119]
	v_mfma_f32_16x16x32_bf16 v[112:115], v[184:187], v[192:195], v[112:115]
	v_mfma_f32_16x16x32_bf16 v[100:103], v[176:179], v[200:203], v[100:103]
	v_mfma_f32_16x16x32_bf16 v[96:99], v[184:187], v[200:203], v[96:99]
	v_mfma_f32_16x16x32_bf16 v[84:87], v[176:179], v[208:211], v[84:87]
	v_mfma_f32_16x16x32_bf16 v[80:83], v[184:187], v[208:211], v[80:83]
	v_mfma_f32_16x16x32_bf16 v[68:71], v[176:179], v[216:219], v[68:71]
	v_mfma_f32_16x16x32_bf16 v[64:67], v[184:187], v[216:219], v[64:67]
	s_setprio 0
	s_barrier
	s_mov_b32 m0, s44
	v_lshl_add_u64 v[220:221], v[220:221], 0, s[10:11]
	s_add_u32 s26, s26, 0x40080
	ds_read_b128 v[188:191], v147 offset:49152
	ds_read_b128 v[192:195], v147 offset:50176
	ds_read_b128 v[196:199], v147 offset:51200
	ds_read_b128 v[200:203], v147 offset:52224
	ds_read_b128 v[204:207], v147 offset:53248
	ds_read_b128 v[208:211], v147 offset:54272
	ds_read_b128 v[212:215], v147 offset:55296
	ds_read_b128 v[216:219], v147 offset:56320
	global_load_lds_dwordx4 v[220:221], off
	v_lshl_add_u64 v[220:221], v[222:223], 0, s[10:11]
	s_mov_b32 m0, s45
	s_addc_u32 s27, s27, 0
	global_load_lds_dwordx4 v[220:221], off
	v_lshl_add_u64 v[220:221], s[26:27], 0, v[130:131]
	s_mov_b32 m0, s46
	s_nop 0
	global_load_lds_dwordx4 v[220:221], off
	v_lshl_add_u64 v[220:221], s[26:27], 0, v[134:135]
	s_mov_b32 m0, s47
	s_nop 0
	global_load_lds_dwordx4 v[220:221], off
	v_lshl_add_u64 v[220:221], v[224:225], 0, s[10:11]
	s_mov_b32 m0, s19
	s_nop 0
	global_load_lds_dwordx4 v[220:221], off
	v_lshl_add_u64 v[220:221], v[226:227], 0, s[10:11]
	s_mov_b32 m0, s33
	s_nop 0
	global_load_lds_dwordx4 v[220:221], off
	s_waitcnt vmcnt(8)
	s_waitcnt lgkmcnt(0)
	s_barrier
	s_setprio 1
	v_mfma_f32_16x16x32_bf16 v[60:63], v[152:155], v[188:191], v[60:63]
	v_mfma_f32_16x16x32_bf16 v[56:59], v[160:163], v[188:191], v[56:59]
	v_mfma_f32_16x16x32_bf16 v[44:47], v[152:155], v[196:199], v[44:47]
	v_mfma_f32_16x16x32_bf16 v[40:43], v[160:163], v[196:199], v[40:43]
	v_mfma_f32_16x16x32_bf16 v[28:31], v[152:155], v[204:207], v[28:31]
	v_mfma_f32_16x16x32_bf16 v[24:27], v[160:163], v[204:207], v[24:27]
	v_mfma_f32_16x16x32_bf16 v[12:15], v[152:155], v[212:215], v[12:15]
	v_mfma_f32_16x16x32_bf16 v[8:11], v[160:163], v[212:215], v[8:11]
	v_mfma_f32_16x16x32_bf16 v[60:63], v[156:159], v[192:195], v[60:63]
	v_mfma_f32_16x16x32_bf16 v[56:59], v[168:171], v[192:195], v[56:59]
	v_mfma_f32_16x16x32_bf16 v[44:47], v[156:159], v[200:203], v[44:47]
	v_mfma_f32_16x16x32_bf16 v[40:43], v[168:171], v[200:203], v[40:43]
	v_mfma_f32_16x16x32_bf16 v[28:31], v[156:159], v[208:211], v[28:31]
	v_mfma_f32_16x16x32_bf16 v[24:27], v[168:171], v[208:211], v[24:27]
	v_mfma_f32_16x16x32_bf16 v[12:15], v[156:159], v[216:219], v[12:15]
	v_mfma_f32_16x16x32_bf16 v[8:11], v[168:171], v[216:219], v[8:11]
	v_mfma_f32_16x16x32_bf16 v[52:55], v[172:175], v[188:191], v[52:55]
	v_mfma_f32_16x16x32_bf16 v[48:51], v[180:183], v[188:191], v[48:51]
	v_mfma_f32_16x16x32_bf16 v[36:39], v[172:175], v[196:199], v[36:39]
	v_mfma_f32_16x16x32_bf16 v[32:35], v[180:183], v[196:199], v[32:35]
	v_mfma_f32_16x16x32_bf16 v[20:23], v[172:175], v[204:207], v[20:23]
	v_mfma_f32_16x16x32_bf16 v[16:19], v[180:183], v[204:207], v[16:19]
	v_mfma_f32_16x16x32_bf16 v[4:7], v[172:175], v[212:215], v[4:7]
	v_mfma_f32_16x16x32_bf16 v[0:3], v[180:183], v[212:215], v[0:3]
	v_mfma_f32_16x16x32_bf16 v[52:55], v[176:179], v[192:195], v[52:55]
	v_mfma_f32_16x16x32_bf16 v[48:51], v[184:187], v[192:195], v[48:51]
	v_mfma_f32_16x16x32_bf16 v[36:39], v[176:179], v[200:203], v[36:39]
	v_mfma_f32_16x16x32_bf16 v[32:35], v[184:187], v[200:203], v[32:35]
	v_mfma_f32_16x16x32_bf16 v[20:23], v[176:179], v[208:211], v[20:23]
	v_mfma_f32_16x16x32_bf16 v[16:19], v[184:187], v[208:211], v[16:19]
	v_mfma_f32_16x16x32_bf16 v[4:7], v[176:179], v[216:219], v[4:7]
	v_mfma_f32_16x16x32_bf16 v[0:3], v[184:187], v[216:219], v[0:3]
	s_add_i32 s34, s34, 2
	s_add_u32 s24, s24, 0x100
	s_addc_u32 s25, s25, 0
	s_cmp_gt_u32 s34, 13
	s_setprio 0
	s_barrier
	s_cbranch_scc0 .LBB0_131
	s_cmpk_lt_u32 s2, 0x100
	s_cbranch_scc0 .LBB0_134
	s_barrier

.LBB0_681:
	ds_read_b128 v[128:131], v174
	ds_read_b128 v[132:135], v174 offset:1024
	ds_read_b128 v[160:163], v174 offset:2048
	ds_read_b128 v[178:181], v174 offset:3072
	ds_read_b128 v[182:185], v175
	ds_read_b128 v[186:189], v175 offset:1024
	ds_read_b128 v[190:193], v175 offset:2048
	ds_read_b128 v[194:197], v175 offset:3072
	s_add_u32 s10, s8, 0xfffc0080
	s_addc_u32 s11, s9, -1
	s_cmp_eq_u32 s48, 12
	s_cselect_b32 s13, s2, s11
	s_cselect_b32 s12, s7, s10
	s_cselect_b32 s11, s24, s42
	s_cselect_b32 s10, s33, s34
	v_lshl_add_u64 v[230:231], s[8:9], 0, v[152:153]
	s_add_i32 m0, s41, 0xc000
	ds_read_b128 v[198:201], v176
	ds_read_b128 v[202:205], v176 offset:1024
	ds_read_b128 v[206:209], v176 offset:2048
	ds_read_b128 v[210:213], v176 offset:3072
	ds_read_b128 v[214:217], v176 offset:4096
	ds_read_b128 v[218:221], v176 offset:5120
	ds_read_b128 v[222:225], v176 offset:6144
	ds_read_b128 v[226:229], v176 offset:7168
	global_load_lds_dwordx4 v[230:231], off
	v_lshl_add_u64 v[230:231], s[8:9], 0, v[154:155]
	s_add_i32 m0, s41, 0xe000
	s_nop 0
	global_load_lds_dwordx4 v[230:231], off
	s_waitcnt vmcnt(8)
	s_waitcnt lgkmcnt(0)
	s_barrier
	s_setprio 1
	v_mfma_f32_16x16x32_bf16 v[124:127], v[128:131], v[198:201], v[124:127]
	v_mfma_f32_16x16x32_bf16 v[120:123], v[160:163], v[198:201], v[120:123]
	v_mfma_f32_16x16x32_bf16 v[108:111], v[128:131], v[206:209], v[108:111]
	v_mfma_f32_16x16x32_bf16 v[104:107], v[160:163], v[206:209], v[104:107]
	v_mfma_f32_16x16x32_bf16 v[92:95], v[128:131], v[214:217], v[92:95]
	v_mfma_f32_16x16x32_bf16 v[88:91], v[160:163], v[214:217], v[88:91]
	v_mfma_f32_16x16x32_bf16 v[76:79], v[128:131], v[222:225], v[76:79]
	v_mfma_f32_16x16x32_bf16 v[72:75], v[160:163], v[222:225], v[72:75]
	v_mfma_f32_16x16x32_bf16 v[124:127], v[132:135], v[202:205], v[124:127]
	v_mfma_f32_16x16x32_bf16 v[120:123], v[178:181], v[202:205], v[120:123]
	v_mfma_f32_16x16x32_bf16 v[108:111], v[132:135], v[210:213], v[108:111]
	v_mfma_f32_16x16x32_bf16 v[104:107], v[178:181], v[210:213], v[104:107]
	v_mfma_f32_16x16x32_bf16 v[92:95], v[132:135], v[218:221], v[92:95]
	v_mfma_f32_16x16x32_bf16 v[88:91], v[178:181], v[218:221], v[88:91]
	v_mfma_f32_16x16x32_bf16 v[76:79], v[132:135], v[226:229], v[76:79]
	v_mfma_f32_16x16x32_bf16 v[72:75], v[178:181], v[226:229], v[72:75]
	v_mfma_f32_16x16x32_bf16 v[116:119], v[182:185], v[198:201], v[116:119]
	v_mfma_f32_16x16x32_bf16 v[112:115], v[190:193], v[198:201], v[112:115]
	v_mfma_f32_16x16x32_bf16 v[100:103], v[182:185], v[206:209], v[100:103]
	v_mfma_f32_16x16x32_bf16 v[96:99], v[190:193], v[206:209], v[96:99]
	v_mfma_f32_16x16x32_bf16 v[84:87], v[182:185], v[214:217], v[84:87]
	v_mfma_f32_16x16x32_bf16 v[80:83], v[190:193], v[214:217], v[80:83]
	v_mfma_f32_16x16x32_bf16 v[68:71], v[182:185], v[222:225], v[68:71]
	v_mfma_f32_16x16x32_bf16 v[64:67], v[190:193], v[222:225], v[64:67]
	v_mfma_f32_16x16x32_bf16 v[116:119], v[186:189], v[202:205], v[116:119]
	v_mfma_f32_16x16x32_bf16 v[112:115], v[194:197], v[202:205], v[112:115]
	v_mfma_f32_16x16x32_bf16 v[100:103], v[186:189], v[210:213], v[100:103]
	v_mfma_f32_16x16x32_bf16 v[96:99], v[194:197], v[210:213], v[96:99]
	v_mfma_f32_16x16x32_bf16 v[84:87], v[186:189], v[218:221], v[84:87]
	v_mfma_f32_16x16x32_bf16 v[80:83], v[194:197], v[218:221], v[80:83]
	v_mfma_f32_16x16x32_bf16 v[68:71], v[186:189], v[226:229], v[68:71]
	v_mfma_f32_16x16x32_bf16 v[64:67], v[194:197], v[226:229], v[64:67]
	s_setprio 0
	s_barrier
	s_add_i32 s49, s94, s35
	v_lshl_add_u64 v[230:231], s[10:11], 0, v[142:143]
	s_mov_b32 m0, s49
	ds_read_b128 v[198:201], v176 offset:16384
	ds_read_b128 v[202:205], v176 offset:17408
	ds_read_b128 v[206:209], v176 offset:18432
	ds_read_b128 v[210:213], v176 offset:19456
	ds_read_b128 v[214:217], v176 offset:20480
	ds_read_b128 v[218:221], v176 offset:21504
	ds_read_b128 v[222:225], v176 offset:22528
	ds_read_b128 v[226:229], v176 offset:23552
	global_load_lds_dwordx4 v[230:231], off
	s_add_i32 m0, s49, 0x2000
	s_add_u32 s50, s10, 0x40000
	v_lshl_add_u64 v[232:233], s[10:11], 0, v[146:147]
	s_addc_u32 s51, s11, 0
	s_add_i32 s49, s95, s35
	global_load_lds_dwordx4 v[232:233], off
	v_lshl_add_u64 v[234:235], s[50:51], 0, v[142:143]
	s_mov_b32 m0, s49
	v_lshl_add_u64 v[236:237], s[12:13], 0, v[144:145]
	global_load_lds_dwordx4 v[234:235], off
	v_lshl_add_u64 v[234:235], s[50:51], 0, v[146:147]
	s_add_i32 m0, s49, 0x2000
	s_nop 0
	global_load_lds_dwordx4 v[234:235], off
	v_lshl_add_u64 v[234:235], s[12:13], 0, v[140:141]
	s_mov_b32 m0, s41
	s_nop 0
	global_load_lds_dwordx4 v[234:235], off
	s_mov_b32 m0, s55
	s_nop 0
	global_load_lds_dwordx4 v[236:237], off
	s_waitcnt vmcnt(8)
	s_waitcnt lgkmcnt(0)
	s_barrier
	s_setprio 1
	v_mfma_f32_16x16x32_bf16 v[60:63], v[128:131], v[198:201], v[60:63]
	v_mfma_f32_16x16x32_bf16 v[56:59], v[160:163], v[198:201], v[56:59]
	v_mfma_f32_16x16x32_bf16 v[44:47], v[128:131], v[206:209], v[44:47]
	v_mfma_f32_16x16x32_bf16 v[40:43], v[160:163], v[206:209], v[40:43]
	v_mfma_f32_16x16x32_bf16 v[28:31], v[128:131], v[214:217], v[28:31]
	v_mfma_f32_16x16x32_bf16 v[24:27], v[160:163], v[214:217], v[24:27]
	v_mfma_f32_16x16x32_bf16 v[12:15], v[128:131], v[222:225], v[12:15]
	v_mfma_f32_16x16x32_bf16 v[8:11], v[160:163], v[222:225], v[8:11]
	v_mfma_f32_16x16x32_bf16 v[60:63], v[132:135], v[202:205], v[60:63]
	v_mfma_f32_16x16x32_bf16 v[56:59], v[178:181], v[202:205], v[56:59]
	v_mfma_f32_16x16x32_bf16 v[44:47], v[132:135], v[210:213], v[44:47]
	v_mfma_f32_16x16x32_bf16 v[40:43], v[178:181], v[210:213], v[40:43]
	v_mfma_f32_16x16x32_bf16 v[28:31], v[132:135], v[218:221], v[28:31]
	v_mfma_f32_16x16x32_bf16 v[24:27], v[178:181], v[218:221], v[24:27]
	v_mfma_f32_16x16x32_bf16 v[12:15], v[132:135], v[226:229], v[12:15]
	v_mfma_f32_16x16x32_bf16 v[8:11], v[178:181], v[226:229], v[8:11]
	v_mfma_f32_16x16x32_bf16 v[52:55], v[182:185], v[198:201], v[52:55]
	v_mfma_f32_16x16x32_bf16 v[48:51], v[190:193], v[198:201], v[48:51]
	v_mfma_f32_16x16x32_bf16 v[36:39], v[182:185], v[206:209], v[36:39]
	v_mfma_f32_16x16x32_bf16 v[32:35], v[190:193], v[206:209], v[32:35]
	v_mfma_f32_16x16x32_bf16 v[20:23], v[182:185], v[214:217], v[20:23]
	v_mfma_f32_16x16x32_bf16 v[16:19], v[190:193], v[214:217], v[16:19]
	v_mfma_f32_16x16x32_bf16 v[4:7], v[182:185], v[222:225], v[4:7]
	v_mfma_f32_16x16x32_bf16 v[0:3], v[190:193], v[222:225], v[0:3]
	v_mfma_f32_16x16x32_bf16 v[52:55], v[186:189], v[202:205], v[52:55]
	v_mfma_f32_16x16x32_bf16 v[48:51], v[194:197], v[202:205], v[48:51]
	v_mfma_f32_16x16x32_bf16 v[36:39], v[186:189], v[210:213], v[36:39]
	v_mfma_f32_16x16x32_bf16 v[32:35], v[194:197], v[210:213], v[32:35]
	v_mfma_f32_16x16x32_bf16 v[20:23], v[186:189], v[218:221], v[20:23]
	v_mfma_f32_16x16x32_bf16 v[16:19], v[194:197], v[218:221], v[16:19]
	v_mfma_f32_16x16x32_bf16 v[4:7], v[186:189], v[226:229], v[4:7]
	v_mfma_f32_16x16x32_bf16 v[0:3], v[194:197], v[226:229], v[0:3]
	s_setprio 0
	s_barrier
	s_add_i32 s49, 0, 0x18000
	v_add_u32_e32 v148, s49, v167
	s_add_i32 s50, 0, 0x1c000
	ds_read_b128 v[128:131], v148
	ds_read_b128 v[132:135], v148 offset:1024
	ds_read_b128 v[160:163], v148 offset:2048
	ds_read_b128 v[178:181], v148 offset:3072
	v_add_u32_e32 v148, s50, v167
	ds_read_b128 v[182:185], v148
	ds_read_b128 v[186:189], v148 offset:1024
	ds_read_b128 v[190:193], v148 offset:2048
	ds_read_b128 v[194:197], v148 offset:3072
	s_add_u32 s12, s12, 0x40000
	s_addc_u32 s13, s13, 0
	s_mov_b32 m0, s59
	v_lshl_add_u64 v[238:239], s[12:13], 0, v[140:141]
	ds_read_b128 v[198:201], v176 offset:32768
	ds_read_b128 v[202:205], v176 offset:33792
	ds_read_b128 v[206:209], v176 offset:34816
	ds_read_b128 v[210:213], v176 offset:35840
	ds_read_b128 v[214:217], v176 offset:36864
	ds_read_b128 v[218:221], v176 offset:37888
	ds_read_b128 v[222:225], v176 offset:38912
	ds_read_b128 v[226:229], v176 offset:39936
	global_load_lds_dwordx4 v[238:239], off
	v_lshl_add_u64 v[238:239], s[12:13], 0, v[144:145]
	s_mov_b32 m0, s61
	s_nop 0
	global_load_lds_dwordx4 v[238:239], off
	s_waitcnt vmcnt(8)
	s_waitcnt lgkmcnt(0)
	s_barrier
	s_setprio 1
	v_mfma_f32_16x16x32_bf16 v[124:127], v[128:131], v[198:201], v[124:127]
	v_mfma_f32_16x16x32_bf16 v[120:123], v[160:163], v[198:201], v[120:123]
	v_mfma_f32_16x16x32_bf16 v[108:111], v[128:131], v[206:209], v[108:111]
	v_mfma_f32_16x16x32_bf16 v[104:107], v[160:163], v[206:209], v[104:107]
	v_mfma_f32_16x16x32_bf16 v[92:95], v[128:131], v[214:217], v[92:95]
	v_mfma_f32_16x16x32_bf16 v[88:91], v[160:163], v[214:217], v[88:91]
	v_mfma_f32_16x16x32_bf16 v[76:79], v[128:131], v[222:225], v[76:79]
	v_mfma_f32_16x16x32_bf16 v[72:75], v[160:163], v[222:225], v[72:75]
	v_mfma_f32_16x16x32_bf16 v[124:127], v[132:135], v[202:205], v[124:127]
	v_mfma_f32_16x16x32_bf16 v[120:123], v[178:181], v[202:205], v[120:123]
	v_mfma_f32_16x16x32_bf16 v[108:111], v[132:135], v[210:213], v[108:111]
	v_mfma_f32_16x16x32_bf16 v[104:107], v[178:181], v[210:213], v[104:107]
	v_mfma_f32_16x16x32_bf16 v[92:95], v[132:135], v[218:221], v[92:95]
	v_mfma_f32_16x16x32_bf16 v[88:91], v[178:181], v[218:221], v[88:91]
	v_mfma_f32_16x16x32_bf16 v[76:79], v[132:135], v[226:229], v[76:79]
	v_mfma_f32_16x16x32_bf16 v[72:75], v[178:181], v[226:229], v[72:75]
	v_mfma_f32_16x16x32_bf16 v[116:119], v[182:185], v[198:201], v[116:119]
	v_mfma_f32_16x16x32_bf16 v[112:115], v[190:193], v[198:201], v[112:115]
	v_mfma_f32_16x16x32_bf16 v[100:103], v[182:185], v[206:209], v[100:103]
	v_mfma_f32_16x16x32_bf16 v[96:99], v[190:193], v[206:209], v[96:99]
	v_mfma_f32_16x16x32_bf16 v[84:87], v[182:185], v[214:217], v[84:87]
	v_mfma_f32_16x16x32_bf16 v[80:83], v[190:193], v[214:217], v[80:83]
	v_mfma_f32_16x16x32_bf16 v[68:71], v[182:185], v[222:225], v[68:71]
	v_mfma_f32_16x16x32_bf16 v[64:67], v[190:193], v[222:225], v[64:67]
	v_mfma_f32_16x16x32_bf16 v[116:119], v[186:189], v[202:205], v[116:119]
	v_mfma_f32_16x16x32_bf16 v[112:115], v[194:197], v[202:205], v[112:115]
	v_mfma_f32_16x16x32_bf16 v[100:103], v[186:189], v[210:213], v[100:103]
	v_mfma_f32_16x16x32_bf16 v[96:99], v[194:197], v[210:213], v[96:99]
	v_mfma_f32_16x16x32_bf16 v[84:87], v[186:189], v[218:221], v[84:87]
	v_mfma_f32_16x16x32_bf16 v[80:83], v[194:197], v[218:221], v[80:83]
	v_mfma_f32_16x16x32_bf16 v[68:71], v[186:189], v[226:229], v[68:71]
	v_mfma_f32_16x16x32_bf16 v[64:67], v[194:197], v[226:229], v[64:67]
	s_setprio 0
	s_barrier
	s_add_i32 s12, s49, s35
	v_lshl_add_u64 v[230:231], v[230:231], 0, s[36:37]
	s_mov_b32 m0, s12
	ds_read_b128 v[198:201], v176 offset:49152
	ds_read_b128 v[202:205], v176 offset:50176
	ds_read_b128 v[206:209], v176 offset:51200
	ds_read_b128 v[210:213], v176 offset:52224
	ds_read_b128 v[214:217], v176 offset:53248
	ds_read_b128 v[218:221], v176 offset:54272
	ds_read_b128 v[222:225], v176 offset:55296
	ds_read_b128 v[226:229], v176 offset:56320
	global_load_lds_dwordx4 v[230:231], off
	s_add_i32 m0, s12, 0x2000
	s_add_u32 s10, s10, 0x40080
	v_lshl_add_u64 v[230:231], v[232:233], 0, s[36:37]
	s_addc_u32 s11, s11, 0
	s_add_i32 s12, s50, s35
	global_load_lds_dwordx4 v[230:231], off
	v_lshl_add_u64 v[230:231], s[10:11], 0, v[142:143]
	s_mov_b32 m0, s12
	s_nop 0
	global_load_lds_dwordx4 v[230:231], off
	v_lshl_add_u64 v[230:231], s[10:11], 0, v[146:147]
	s_add_i32 m0, s12, 0x2000
	s_nop 0
	global_load_lds_dwordx4 v[230:231], off
	v_lshl_add_u64 v[230:231], v[234:235], 0, s[36:37]
	s_mov_b32 m0, s82
	s_nop 0
	global_load_lds_dwordx4 v[230:231], off
	v_lshl_add_u64 v[230:231], v[236:237], 0, s[36:37]
	s_mov_b32 m0, s83
	s_nop 0
	global_load_lds_dwordx4 v[230:231], off
	s_waitcnt vmcnt(8)
	s_waitcnt lgkmcnt(0)
	s_barrier
	s_setprio 1
	v_mfma_f32_16x16x32_bf16 v[60:63], v[128:131], v[198:201], v[60:63]
	v_mfma_f32_16x16x32_bf16 v[56:59], v[160:163], v[198:201], v[56:59]
	v_mfma_f32_16x16x32_bf16 v[44:47], v[128:131], v[206:209], v[44:47]
	v_mfma_f32_16x16x32_bf16 v[40:43], v[160:163], v[206:209], v[40:43]
	v_mfma_f32_16x16x32_bf16 v[28:31], v[128:131], v[214:217], v[28:31]
	v_mfma_f32_16x16x32_bf16 v[24:27], v[160:163], v[214:217], v[24:27]
	v_mfma_f32_16x16x32_bf16 v[12:15], v[128:131], v[222:225], v[12:15]
	v_mfma_f32_16x16x32_bf16 v[8:11], v[160:163], v[222:225], v[8:11]
	v_mfma_f32_16x16x32_bf16 v[60:63], v[132:135], v[202:205], v[60:63]
	v_mfma_f32_16x16x32_bf16 v[56:59], v[178:181], v[202:205], v[56:59]
	v_mfma_f32_16x16x32_bf16 v[44:47], v[132:135], v[210:213], v[44:47]
	v_mfma_f32_16x16x32_bf16 v[40:43], v[178:181], v[210:213], v[40:43]
	v_mfma_f32_16x16x32_bf16 v[28:31], v[132:135], v[218:221], v[28:31]
	v_mfma_f32_16x16x32_bf16 v[24:27], v[178:181], v[218:221], v[24:27]
	v_mfma_f32_16x16x32_bf16 v[12:15], v[132:135], v[226:229], v[12:15]
	v_mfma_f32_16x16x32_bf16 v[8:11], v[178:181], v[226:229], v[8:11]
	v_mfma_f32_16x16x32_bf16 v[52:55], v[182:185], v[198:201], v[52:55]
	v_mfma_f32_16x16x32_bf16 v[48:51], v[190:193], v[198:201], v[48:51]
	v_mfma_f32_16x16x32_bf16 v[36:39], v[182:185], v[206:209], v[36:39]
	v_mfma_f32_16x16x32_bf16 v[32:35], v[190:193], v[206:209], v[32:35]
	v_mfma_f32_16x16x32_bf16 v[20:23], v[182:185], v[214:217], v[20:23]
	v_mfma_f32_16x16x32_bf16 v[16:19], v[190:193], v[214:217], v[16:19]
	v_mfma_f32_16x16x32_bf16 v[4:7], v[182:185], v[222:225], v[4:7]
	v_mfma_f32_16x16x32_bf16 v[0:3], v[190:193], v[222:225], v[0:3]
	v_mfma_f32_16x16x32_bf16 v[52:55], v[186:189], v[202:205], v[52:55]
	v_mfma_f32_16x16x32_bf16 v[48:51], v[194:197], v[202:205], v[48:51]
	v_mfma_f32_16x16x32_bf16 v[36:39], v[186:189], v[210:213], v[36:39]
	v_mfma_f32_16x16x32_bf16 v[32:35], v[194:197], v[210:213], v[32:35]
	v_mfma_f32_16x16x32_bf16 v[20:23], v[186:189], v[218:221], v[20:23]
	v_mfma_f32_16x16x32_bf16 v[16:19], v[194:197], v[218:221], v[16:19]
	v_mfma_f32_16x16x32_bf16 v[4:7], v[186:189], v[226:229], v[4:7]
	v_mfma_f32_16x16x32_bf16 v[0:3], v[194:197], v[226:229], v[0:3]
	s_add_i32 s48, s48, 2
	s_add_u32 s8, s8, 0x100
	s_addc_u32 s9, s9, 0
	s_add_u32 s34, s34, 0x100
	s_addc_u32 s42, s42, 0
	s_cmp_gt_u32 s48, 13
	s_setprio 0
	s_barrier
	s_cbranch_scc0 .LBB0_681
	s_and_b64 vcc, exec, s[38:39]
	s_cbranch_vccz .LBB0_684
	s_barrier

.LBB0_1506:
	ds_read_b128 v[166:169], v159
	ds_read_b128 v[170:173], v159 offset:1024
	ds_read_b128 v[174:177], v159 offset:2048
	ds_read_b128 v[178:181], v159 offset:3072
	ds_read_b128 v[182:185], v160
	ds_read_b128 v[186:189], v160 offset:1024
	ds_read_b128 v[190:193], v160 offset:2048
	ds_read_b128 v[194:197], v160 offset:3072
	s_add_i32 s49, s48, 2
	s_add_u32 s50, s68, 0xfffc0080
	s_addc_u32 s51, s69, -1
	s_cmp_eq_u32 s33, s48
	s_cselect_b32 s73, s61, s51
	s_cselect_b32 s72, s60, s50
	s_cselect_b32 s71, s63, s42
	s_cselect_b32 s70, s62, s34
	v_lshl_add_u64 v[146:147], s[68:69], 0, v[142:143]
	s_add_i32 m0, s14, 0xc000
	ds_read_b128 v[198:201], v161
	ds_read_b128 v[202:205], v161 offset:1024
	ds_read_b128 v[206:209], v161 offset:2048
	ds_read_b128 v[210:213], v161 offset:3072
	ds_read_b128 v[214:217], v161 offset:4096
	ds_read_b128 v[218:221], v161 offset:5120
	ds_read_b128 v[222:225], v161 offset:6144
	ds_read_b128 v[226:229], v161 offset:7168
	global_load_lds_dwordx4 v[146:147], off
	v_lshl_add_u64 v[146:147], s[68:69], 0, v[144:145]
	s_add_i32 m0, s14, 0xe000
	s_nop 0
	global_load_lds_dwordx4 v[146:147], off
	s_waitcnt vmcnt(8)
	s_waitcnt lgkmcnt(0)
	s_barrier
	s_setprio 1
	v_mfma_f32_16x16x32_bf16 v[124:127], v[166:169], v[198:201], v[124:127]
	v_mfma_f32_16x16x32_bf16 v[120:123], v[174:177], v[198:201], v[120:123]
	v_mfma_f32_16x16x32_bf16 v[108:111], v[166:169], v[206:209], v[108:111]
	v_mfma_f32_16x16x32_bf16 v[104:107], v[174:177], v[206:209], v[104:107]
	v_mfma_f32_16x16x32_bf16 v[92:95], v[166:169], v[214:217], v[92:95]
	v_mfma_f32_16x16x32_bf16 v[88:91], v[174:177], v[214:217], v[88:91]
	v_mfma_f32_16x16x32_bf16 v[76:79], v[166:169], v[222:225], v[76:79]
	v_mfma_f32_16x16x32_bf16 v[72:75], v[174:177], v[222:225], v[72:75]
	v_mfma_f32_16x16x32_bf16 v[124:127], v[170:173], v[202:205], v[124:127]
	v_mfma_f32_16x16x32_bf16 v[120:123], v[178:181], v[202:205], v[120:123]
	v_mfma_f32_16x16x32_bf16 v[108:111], v[170:173], v[210:213], v[108:111]
	v_mfma_f32_16x16x32_bf16 v[104:107], v[178:181], v[210:213], v[104:107]
	v_mfma_f32_16x16x32_bf16 v[92:95], v[170:173], v[218:221], v[92:95]
	v_mfma_f32_16x16x32_bf16 v[88:91], v[178:181], v[218:221], v[88:91]
	v_mfma_f32_16x16x32_bf16 v[76:79], v[170:173], v[226:229], v[76:79]
	v_mfma_f32_16x16x32_bf16 v[72:75], v[178:181], v[226:229], v[72:75]
	v_mfma_f32_16x16x32_bf16 v[116:119], v[182:185], v[198:201], v[116:119]
	v_mfma_f32_16x16x32_bf16 v[112:115], v[190:193], v[198:201], v[112:115]
	v_mfma_f32_16x16x32_bf16 v[100:103], v[182:185], v[206:209], v[100:103]
	v_mfma_f32_16x16x32_bf16 v[96:99], v[190:193], v[206:209], v[96:99]
	v_mfma_f32_16x16x32_bf16 v[84:87], v[182:185], v[214:217], v[84:87]
	v_mfma_f32_16x16x32_bf16 v[80:83], v[190:193], v[214:217], v[80:83]
	v_mfma_f32_16x16x32_bf16 v[68:71], v[182:185], v[222:225], v[68:71]
	v_mfma_f32_16x16x32_bf16 v[64:67], v[190:193], v[222:225], v[64:67]
	v_mfma_f32_16x16x32_bf16 v[116:119], v[186:189], v[202:205], v[116:119]
	v_mfma_f32_16x16x32_bf16 v[112:115], v[194:197], v[202:205], v[112:115]
	v_mfma_f32_16x16x32_bf16 v[100:103], v[186:189], v[210:213], v[100:103]
	v_mfma_f32_16x16x32_bf16 v[96:99], v[194:197], v[210:213], v[96:99]
	v_mfma_f32_16x16x32_bf16 v[84:87], v[186:189], v[218:221], v[84:87]
	v_mfma_f32_16x16x32_bf16 v[80:83], v[194:197], v[218:221], v[80:83]
	v_mfma_f32_16x16x32_bf16 v[68:71], v[186:189], v[226:229], v[68:71]
	v_mfma_f32_16x16x32_bf16 v[64:67], v[194:197], v[226:229], v[64:67]
	s_setprio 0
	s_barrier
	s_add_i32 s48, s52, s3
	v_lshl_add_u64 v[146:147], s[70:71], 0, v[132:133]
	s_mov_b32 m0, s48
	ds_read_b128 v[198:201], v161 offset:16384
	ds_read_b128 v[202:205], v161 offset:17408
	ds_read_b128 v[206:209], v161 offset:18432
	ds_read_b128 v[210:213], v161 offset:19456
	ds_read_b128 v[214:217], v161 offset:20480
	ds_read_b128 v[218:221], v161 offset:21504
	ds_read_b128 v[222:225], v161 offset:22528
	ds_read_b128 v[226:229], v161 offset:23552
	global_load_lds_dwordx4 v[146:147], off
	s_add_i32 m0, s48, 0x2000
	s_add_u32 s50, s70, 0x40000
	v_lshl_add_u64 v[162:163], s[70:71], 0, v[136:137]
	s_addc_u32 s51, s71, 0
	s_add_i32 s48, s53, s3
	global_load_lds_dwordx4 v[162:163], off
	v_lshl_add_u64 v[230:231], s[50:51], 0, v[132:133]
	s_mov_b32 m0, s48
	v_lshl_add_u64 v[232:233], s[72:73], 0, v[134:135]
	global_load_lds_dwordx4 v[230:231], off
	v_lshl_add_u64 v[230:231], s[50:51], 0, v[136:137]
	s_add_i32 m0, s48, 0x2000
	s_nop 0
	global_load_lds_dwordx4 v[230:231], off
	v_lshl_add_u64 v[230:231], s[72:73], 0, v[130:131]
	s_mov_b32 m0, s14
	s_nop 0
	global_load_lds_dwordx4 v[230:231], off
	s_mov_b32 m0, s15
	s_nop 0
	global_load_lds_dwordx4 v[232:233], off
	s_waitcnt vmcnt(8)
	s_waitcnt lgkmcnt(0)
	s_barrier
	s_setprio 1
	v_mfma_f32_16x16x32_bf16 v[60:63], v[166:169], v[198:201], v[60:63]
	v_mfma_f32_16x16x32_bf16 v[56:59], v[174:177], v[198:201], v[56:59]
	v_mfma_f32_16x16x32_bf16 v[44:47], v[166:169], v[206:209], v[44:47]
	v_mfma_f32_16x16x32_bf16 v[40:43], v[174:177], v[206:209], v[40:43]
	v_mfma_f32_16x16x32_bf16 v[28:31], v[166:169], v[214:217], v[28:31]
	v_mfma_f32_16x16x32_bf16 v[24:27], v[174:177], v[214:217], v[24:27]
	v_mfma_f32_16x16x32_bf16 v[12:15], v[166:169], v[222:225], v[12:15]
	v_mfma_f32_16x16x32_bf16 v[8:11], v[174:177], v[222:225], v[8:11]
	v_mfma_f32_16x16x32_bf16 v[60:63], v[170:173], v[202:205], v[60:63]
	v_mfma_f32_16x16x32_bf16 v[56:59], v[178:181], v[202:205], v[56:59]
	v_mfma_f32_16x16x32_bf16 v[44:47], v[170:173], v[210:213], v[44:47]
	v_mfma_f32_16x16x32_bf16 v[40:43], v[178:181], v[210:213], v[40:43]
	v_mfma_f32_16x16x32_bf16 v[28:31], v[170:173], v[218:221], v[28:31]
	v_mfma_f32_16x16x32_bf16 v[24:27], v[178:181], v[218:221], v[24:27]
	v_mfma_f32_16x16x32_bf16 v[12:15], v[170:173], v[226:229], v[12:15]
	v_mfma_f32_16x16x32_bf16 v[8:11], v[178:181], v[226:229], v[8:11]
	v_mfma_f32_16x16x32_bf16 v[52:55], v[182:185], v[198:201], v[52:55]
	v_mfma_f32_16x16x32_bf16 v[48:51], v[190:193], v[198:201], v[48:51]
	v_mfma_f32_16x16x32_bf16 v[36:39], v[182:185], v[206:209], v[36:39]
	v_mfma_f32_16x16x32_bf16 v[32:35], v[190:193], v[206:209], v[32:35]
	v_mfma_f32_16x16x32_bf16 v[20:23], v[182:185], v[214:217], v[20:23]
	v_mfma_f32_16x16x32_bf16 v[16:19], v[190:193], v[214:217], v[16:19]
	v_mfma_f32_16x16x32_bf16 v[4:7], v[182:185], v[222:225], v[4:7]
	v_mfma_f32_16x16x32_bf16 v[0:3], v[190:193], v[222:225], v[0:3]
	v_mfma_f32_16x16x32_bf16 v[52:55], v[186:189], v[202:205], v[52:55]
	v_mfma_f32_16x16x32_bf16 v[48:51], v[194:197], v[202:205], v[48:51]
	v_mfma_f32_16x16x32_bf16 v[36:39], v[186:189], v[210:213], v[36:39]
	v_mfma_f32_16x16x32_bf16 v[32:35], v[194:197], v[210:213], v[32:35]
	v_mfma_f32_16x16x32_bf16 v[20:23], v[186:189], v[218:221], v[20:23]
	v_mfma_f32_16x16x32_bf16 v[16:19], v[194:197], v[218:221], v[16:19]
	v_mfma_f32_16x16x32_bf16 v[4:7], v[186:189], v[226:229], v[4:7]
	v_mfma_f32_16x16x32_bf16 v[0:3], v[194:197], v[226:229], v[0:3]
	s_setprio 0
	s_barrier
	s_add_i32 s48, 0, 0x18000
	v_add_u32_e32 v138, s48, v141
	s_add_i32 s55, 0, 0x1c000
	ds_read_b128 v[166:169], v138
	ds_read_b128 v[170:173], v138 offset:1024
	ds_read_b128 v[174:177], v138 offset:2048
	ds_read_b128 v[178:181], v138 offset:3072
	v_add_u32_e32 v138, s55, v141
	ds_read_b128 v[182:185], v138
	ds_read_b128 v[186:189], v138 offset:1024
	ds_read_b128 v[190:193], v138 offset:2048
	ds_read_b128 v[194:197], v138 offset:3072
	s_add_u32 s50, s72, 0x40000
	s_addc_u32 s51, s73, 0
	s_mov_b32 m0, s18
	v_lshl_add_u64 v[234:235], s[50:51], 0, v[130:131]
	ds_read_b128 v[198:201], v161 offset:32768
	ds_read_b128 v[202:205], v161 offset:33792
	ds_read_b128 v[206:209], v161 offset:34816
	ds_read_b128 v[210:213], v161 offset:35840
	ds_read_b128 v[214:217], v161 offset:36864
	ds_read_b128 v[218:221], v161 offset:37888
	ds_read_b128 v[222:225], v161 offset:38912
	ds_read_b128 v[226:229], v161 offset:39936
	global_load_lds_dwordx4 v[234:235], off
	v_lshl_add_u64 v[234:235], s[50:51], 0, v[134:135]
	s_mov_b32 m0, s19
	s_nop 0
	global_load_lds_dwordx4 v[234:235], off
	s_waitcnt vmcnt(8)
	s_waitcnt lgkmcnt(0)
	s_barrier
	s_setprio 1
	v_mfma_f32_16x16x32_bf16 v[124:127], v[166:169], v[198:201], v[124:127]
	v_mfma_f32_16x16x32_bf16 v[120:123], v[174:177], v[198:201], v[120:123]
	v_mfma_f32_16x16x32_bf16 v[108:111], v[166:169], v[206:209], v[108:111]
	v_mfma_f32_16x16x32_bf16 v[104:107], v[174:177], v[206:209], v[104:107]
	v_mfma_f32_16x16x32_bf16 v[92:95], v[166:169], v[214:217], v[92:95]
	v_mfma_f32_16x16x32_bf16 v[88:91], v[174:177], v[214:217], v[88:91]
	v_mfma_f32_16x16x32_bf16 v[76:79], v[166:169], v[222:225], v[76:79]
	v_mfma_f32_16x16x32_bf16 v[72:75], v[174:177], v[222:225], v[72:75]
	v_mfma_f32_16x16x32_bf16 v[124:127], v[170:173], v[202:205], v[124:127]
	v_mfma_f32_16x16x32_bf16 v[120:123], v[178:181], v[202:205], v[120:123]
	v_mfma_f32_16x16x32_bf16 v[108:111], v[170:173], v[210:213], v[108:111]
	v_mfma_f32_16x16x32_bf16 v[104:107], v[178:181], v[210:213], v[104:107]
	v_mfma_f32_16x16x32_bf16 v[92:95], v[170:173], v[218:221], v[92:95]
	v_mfma_f32_16x16x32_bf16 v[88:91], v[178:181], v[218:221], v[88:91]
	v_mfma_f32_16x16x32_bf16 v[76:79], v[170:173], v[226:229], v[76:79]
	v_mfma_f32_16x16x32_bf16 v[72:75], v[178:181], v[226:229], v[72:75]
	v_mfma_f32_16x16x32_bf16 v[116:119], v[182:185], v[198:201], v[116:119]
	v_mfma_f32_16x16x32_bf16 v[112:115], v[190:193], v[198:201], v[112:115]
	v_mfma_f32_16x16x32_bf16 v[100:103], v[182:185], v[206:209], v[100:103]
	v_mfma_f32_16x16x32_bf16 v[96:99], v[190:193], v[206:209], v[96:99]
	v_mfma_f32_16x16x32_bf16 v[84:87], v[182:185], v[214:217], v[84:87]
	v_mfma_f32_16x16x32_bf16 v[80:83], v[190:193], v[214:217], v[80:83]
	v_mfma_f32_16x16x32_bf16 v[68:71], v[182:185], v[222:225], v[68:71]
	v_mfma_f32_16x16x32_bf16 v[64:67], v[190:193], v[222:225], v[64:67]
	v_mfma_f32_16x16x32_bf16 v[116:119], v[186:189], v[202:205], v[116:119]
	v_mfma_f32_16x16x32_bf16 v[112:115], v[194:197], v[202:205], v[112:115]
	v_mfma_f32_16x16x32_bf16 v[100:103], v[186:189], v[210:213], v[100:103]
	v_mfma_f32_16x16x32_bf16 v[96:99], v[194:197], v[210:213], v[96:99]
	v_mfma_f32_16x16x32_bf16 v[84:87], v[186:189], v[218:221], v[84:87]
	v_mfma_f32_16x16x32_bf16 v[80:83], v[194:197], v[218:221], v[80:83]
	v_mfma_f32_16x16x32_bf16 v[68:71], v[186:189], v[226:229], v[68:71]
	v_mfma_f32_16x16x32_bf16 v[64:67], v[194:197], v[226:229], v[64:67]
	s_setprio 0
	s_barrier
	s_add_i32 s48, s48, s3
	v_lshl_add_u64 v[146:147], v[146:147], 0, s[26:27]
	s_mov_b32 m0, s48
	ds_read_b128 v[198:201], v161 offset:49152
	ds_read_b128 v[202:205], v161 offset:50176
	ds_read_b128 v[206:209], v161 offset:51200
	ds_read_b128 v[210:213], v161 offset:52224
	ds_read_b128 v[214:217], v161 offset:53248
	ds_read_b128 v[218:221], v161 offset:54272
	ds_read_b128 v[222:225], v161 offset:55296
	ds_read_b128 v[226:229], v161 offset:56320
	global_load_lds_dwordx4 v[146:147], off
	s_add_i32 m0, s48, 0x2000
	s_add_u32 s50, s70, 0x40080
	v_lshl_add_u64 v[146:147], v[162:163], 0, s[26:27]
	s_addc_u32 s51, s71, 0
	s_add_i32 s48, s55, s3
	global_load_lds_dwordx4 v[146:147], off
	v_lshl_add_u64 v[146:147], s[50:51], 0, v[132:133]
	s_mov_b32 m0, s48
	s_nop 0
	global_load_lds_dwordx4 v[146:147], off
	v_lshl_add_u64 v[146:147], s[50:51], 0, v[136:137]
	s_add_i32 m0, s48, 0x2000
	s_nop 0
	global_load_lds_dwordx4 v[146:147], off
	v_lshl_add_u64 v[146:147], v[230:231], 0, s[26:27]
	s_mov_b32 m0, s43
	s_nop 0
	global_load_lds_dwordx4 v[146:147], off
	v_lshl_add_u64 v[146:147], v[232:233], 0, s[26:27]
	s_mov_b32 m0, s44
	s_nop 0
	global_load_lds_dwordx4 v[146:147], off
	s_waitcnt vmcnt(8)
	s_waitcnt lgkmcnt(0)
	s_barrier
	s_setprio 1
	v_mfma_f32_16x16x32_bf16 v[60:63], v[166:169], v[198:201], v[60:63]
	v_mfma_f32_16x16x32_bf16 v[56:59], v[174:177], v[198:201], v[56:59]
	v_mfma_f32_16x16x32_bf16 v[44:47], v[166:169], v[206:209], v[44:47]
	v_mfma_f32_16x16x32_bf16 v[40:43], v[174:177], v[206:209], v[40:43]
	v_mfma_f32_16x16x32_bf16 v[28:31], v[166:169], v[214:217], v[28:31]
	v_mfma_f32_16x16x32_bf16 v[24:27], v[174:177], v[214:217], v[24:27]
	v_mfma_f32_16x16x32_bf16 v[12:15], v[166:169], v[222:225], v[12:15]
	v_mfma_f32_16x16x32_bf16 v[8:11], v[174:177], v[222:225], v[8:11]
	v_mfma_f32_16x16x32_bf16 v[60:63], v[170:173], v[202:205], v[60:63]
	v_mfma_f32_16x16x32_bf16 v[56:59], v[178:181], v[202:205], v[56:59]
	v_mfma_f32_16x16x32_bf16 v[44:47], v[170:173], v[210:213], v[44:47]
	v_mfma_f32_16x16x32_bf16 v[40:43], v[178:181], v[210:213], v[40:43]
	v_mfma_f32_16x16x32_bf16 v[28:31], v[170:173], v[218:221], v[28:31]
	v_mfma_f32_16x16x32_bf16 v[24:27], v[178:181], v[218:221], v[24:27]
	v_mfma_f32_16x16x32_bf16 v[12:15], v[170:173], v[226:229], v[12:15]
	v_mfma_f32_16x16x32_bf16 v[8:11], v[178:181], v[226:229], v[8:11]
	v_mfma_f32_16x16x32_bf16 v[52:55], v[182:185], v[198:201], v[52:55]
	v_mfma_f32_16x16x32_bf16 v[48:51], v[190:193], v[198:201], v[48:51]
	v_mfma_f32_16x16x32_bf16 v[36:39], v[182:185], v[206:209], v[36:39]
	v_mfma_f32_16x16x32_bf16 v[32:35], v[190:193], v[206:209], v[32:35]
	v_mfma_f32_16x16x32_bf16 v[20:23], v[182:185], v[214:217], v[20:23]
	v_mfma_f32_16x16x32_bf16 v[16:19], v[190:193], v[214:217], v[16:19]
	v_mfma_f32_16x16x32_bf16 v[4:7], v[182:185], v[222:225], v[4:7]
	v_mfma_f32_16x16x32_bf16 v[0:3], v[190:193], v[222:225], v[0:3]
	v_mfma_f32_16x16x32_bf16 v[52:55], v[186:189], v[202:205], v[52:55]
	v_mfma_f32_16x16x32_bf16 v[48:51], v[194:197], v[202:205], v[48:51]
	v_mfma_f32_16x16x32_bf16 v[36:39], v[186:189], v[210:213], v[36:39]
	v_mfma_f32_16x16x32_bf16 v[32:35], v[194:197], v[210:213], v[32:35]
	v_mfma_f32_16x16x32_bf16 v[20:23], v[186:189], v[218:221], v[20:23]
	v_mfma_f32_16x16x32_bf16 v[16:19], v[194:197], v[218:221], v[16:19]
	v_mfma_f32_16x16x32_bf16 v[4:7], v[186:189], v[226:229], v[4:7]
	v_mfma_f32_16x16x32_bf16 v[0:3], v[194:197], v[226:229], v[0:3]
	s_add_u32 s68, s68, 0x100
	s_addc_u32 s69, s69, 0
	s_add_u32 s34, s34, 0x100
	s_addc_u32 s42, s42, 0
	s_cmp_ge_u32 s49, s2
	s_mov_b32 s48, s49
	s_setprio 0
	s_barrier
	s_cbranch_scc0 .LBB0_1506
	s_xor_b64 s[66:67], s[66:67], -1
	s_and_b64 vcc, exec, s[36:37]
	s_cbranch_vccz .LBB0_1528

.LBB0_1658:
	ds_read_b128 v[152:155], v149
	ds_read_b128 v[156:159], v149 offset:1024
	ds_read_b128 v[160:163], v149 offset:2048
	ds_read_b128 v[166:169], v149 offset:3072
	ds_read_b128 v[170:173], v150
	ds_read_b128 v[174:177], v150 offset:1024
	ds_read_b128 v[178:181], v150 offset:2048
	ds_read_b128 v[182:185], v150 offset:3072
	s_add_u32 s50, s58, 0xfffc0080
	s_addc_u32 s51, s59, -1
	s_cmp_eq_u32 s49, 12
	s_cselect_b32 s63, s33, s51
	s_cselect_b32 s62, s34, s50
	s_cselect_b32 s61, s37, s48
	s_cselect_b32 s60, s39, s42
	v_lshl_add_u64 v[218:219], s[58:59], 0, v[140:141]
	s_add_i32 m0, s18, 0xc000
	ds_read_b128 v[186:189], v151
	ds_read_b128 v[190:193], v151 offset:1024
	ds_read_b128 v[194:197], v151 offset:2048
	ds_read_b128 v[198:201], v151 offset:3072
	ds_read_b128 v[202:205], v151 offset:4096
	ds_read_b128 v[206:209], v151 offset:5120
	ds_read_b128 v[210:213], v151 offset:6144
	ds_read_b128 v[214:217], v151 offset:7168
	global_load_lds_dwordx4 v[218:219], off
	v_lshl_add_u64 v[218:219], s[58:59], 0, v[142:143]
	s_add_i32 m0, s18, 0xe000
	s_nop 0
	global_load_lds_dwordx4 v[218:219], off
	s_waitcnt vmcnt(8)
	s_waitcnt lgkmcnt(0)
	s_barrier
	s_setprio 1
	v_mfma_f32_16x16x32_bf16 v[124:127], v[152:155], v[186:189], v[124:127]
	v_mfma_f32_16x16x32_bf16 v[120:123], v[160:163], v[186:189], v[120:123]
	v_mfma_f32_16x16x32_bf16 v[108:111], v[152:155], v[194:197], v[108:111]
	v_mfma_f32_16x16x32_bf16 v[104:107], v[160:163], v[194:197], v[104:107]
	v_mfma_f32_16x16x32_bf16 v[92:95], v[152:155], v[202:205], v[92:95]
	v_mfma_f32_16x16x32_bf16 v[88:91], v[160:163], v[202:205], v[88:91]
	v_mfma_f32_16x16x32_bf16 v[76:79], v[152:155], v[210:213], v[76:79]
	v_mfma_f32_16x16x32_bf16 v[72:75], v[160:163], v[210:213], v[72:75]
	v_mfma_f32_16x16x32_bf16 v[124:127], v[156:159], v[190:193], v[124:127]
	v_mfma_f32_16x16x32_bf16 v[120:123], v[166:169], v[190:193], v[120:123]
	v_mfma_f32_16x16x32_bf16 v[108:111], v[156:159], v[198:201], v[108:111]
	v_mfma_f32_16x16x32_bf16 v[104:107], v[166:169], v[198:201], v[104:107]
	v_mfma_f32_16x16x32_bf16 v[92:95], v[156:159], v[206:209], v[92:95]
	v_mfma_f32_16x16x32_bf16 v[88:91], v[166:169], v[206:209], v[88:91]
	v_mfma_f32_16x16x32_bf16 v[76:79], v[156:159], v[214:217], v[76:79]
	v_mfma_f32_16x16x32_bf16 v[72:75], v[166:169], v[214:217], v[72:75]
	v_mfma_f32_16x16x32_bf16 v[116:119], v[170:173], v[186:189], v[116:119]
	v_mfma_f32_16x16x32_bf16 v[112:115], v[178:181], v[186:189], v[112:115]
	v_mfma_f32_16x16x32_bf16 v[100:103], v[170:173], v[194:197], v[100:103]
	v_mfma_f32_16x16x32_bf16 v[96:99], v[178:181], v[194:197], v[96:99]
	v_mfma_f32_16x16x32_bf16 v[84:87], v[170:173], v[202:205], v[84:87]
	v_mfma_f32_16x16x32_bf16 v[80:83], v[178:181], v[202:205], v[80:83]
	v_mfma_f32_16x16x32_bf16 v[68:71], v[170:173], v[210:213], v[68:71]
	v_mfma_f32_16x16x32_bf16 v[64:67], v[178:181], v[210:213], v[64:67]
	v_mfma_f32_16x16x32_bf16 v[116:119], v[174:177], v[190:193], v[116:119]
	v_mfma_f32_16x16x32_bf16 v[112:115], v[182:185], v[190:193], v[112:115]
	v_mfma_f32_16x16x32_bf16 v[100:103], v[174:177], v[198:201], v[100:103]
	v_mfma_f32_16x16x32_bf16 v[96:99], v[182:185], v[198:201], v[96:99]
	v_mfma_f32_16x16x32_bf16 v[84:87], v[174:177], v[206:209], v[84:87]
	v_mfma_f32_16x16x32_bf16 v[80:83], v[182:185], v[206:209], v[80:83]
	v_mfma_f32_16x16x32_bf16 v[68:71], v[174:177], v[214:217], v[68:71]
	v_mfma_f32_16x16x32_bf16 v[64:67], v[182:185], v[214:217], v[64:67]
	s_setprio 0
	s_barrier
	s_add_i32 s50, s64, s3
	v_lshl_add_u64 v[218:219], s[60:61], 0, v[134:135]
	s_mov_b32 m0, s50
	ds_read_b128 v[186:189], v151 offset:16384
	ds_read_b128 v[190:193], v151 offset:17408
	ds_read_b128 v[194:197], v151 offset:18432
	ds_read_b128 v[198:201], v151 offset:19456
	ds_read_b128 v[202:205], v151 offset:20480
	ds_read_b128 v[206:209], v151 offset:21504
	ds_read_b128 v[210:213], v151 offset:22528
	ds_read_b128 v[214:217], v151 offset:23552
	global_load_lds_dwordx4 v[218:219], off
	s_add_i32 m0, s50, 0x2000
	s_add_u32 s50, s60, 0x40000
	v_lshl_add_u64 v[220:221], s[60:61], 0, v[130:131]
	s_addc_u32 s51, s61, 0
	s_add_i32 s57, s65, s3
	global_load_lds_dwordx4 v[220:221], off
	v_lshl_add_u64 v[222:223], s[50:51], 0, v[134:135]
	s_mov_b32 m0, s57
	v_lshl_add_u64 v[224:225], s[62:63], 0, v[132:133]
	global_load_lds_dwordx4 v[222:223], off
	v_lshl_add_u64 v[222:223], s[50:51], 0, v[130:131]
	s_add_i32 m0, s57, 0x2000
	s_nop 0
	global_load_lds_dwordx4 v[222:223], off
	v_lshl_add_u64 v[222:223], s[62:63], 0, v[136:137]
	s_mov_b32 m0, s18
	s_nop 0
	global_load_lds_dwordx4 v[222:223], off
	s_mov_b32 m0, s19
	s_nop 0
	global_load_lds_dwordx4 v[224:225], off
	s_waitcnt vmcnt(8)
	s_waitcnt lgkmcnt(0)
	s_barrier
	s_setprio 1
	v_mfma_f32_16x16x32_bf16 v[60:63], v[152:155], v[186:189], v[60:63]
	v_mfma_f32_16x16x32_bf16 v[56:59], v[160:163], v[186:189], v[56:59]
	v_mfma_f32_16x16x32_bf16 v[44:47], v[152:155], v[194:197], v[44:47]
	v_mfma_f32_16x16x32_bf16 v[40:43], v[160:163], v[194:197], v[40:43]
	v_mfma_f32_16x16x32_bf16 v[28:31], v[152:155], v[202:205], v[28:31]
	v_mfma_f32_16x16x32_bf16 v[24:27], v[160:163], v[202:205], v[24:27]
	v_mfma_f32_16x16x32_bf16 v[12:15], v[152:155], v[210:213], v[12:15]
	v_mfma_f32_16x16x32_bf16 v[8:11], v[160:163], v[210:213], v[8:11]
	v_mfma_f32_16x16x32_bf16 v[60:63], v[156:159], v[190:193], v[60:63]
	v_mfma_f32_16x16x32_bf16 v[56:59], v[166:169], v[190:193], v[56:59]
	v_mfma_f32_16x16x32_bf16 v[44:47], v[156:159], v[198:201], v[44:47]
	v_mfma_f32_16x16x32_bf16 v[40:43], v[166:169], v[198:201], v[40:43]
	v_mfma_f32_16x16x32_bf16 v[28:31], v[156:159], v[206:209], v[28:31]
	v_mfma_f32_16x16x32_bf16 v[24:27], v[166:169], v[206:209], v[24:27]
	v_mfma_f32_16x16x32_bf16 v[12:15], v[156:159], v[214:217], v[12:15]
	v_mfma_f32_16x16x32_bf16 v[8:11], v[166:169], v[214:217], v[8:11]
	v_mfma_f32_16x16x32_bf16 v[52:55], v[170:173], v[186:189], v[52:55]
	v_mfma_f32_16x16x32_bf16 v[48:51], v[178:181], v[186:189], v[48:51]
	v_mfma_f32_16x16x32_bf16 v[36:39], v[170:173], v[194:197], v[36:39]
	v_mfma_f32_16x16x32_bf16 v[32:35], v[178:181], v[194:197], v[32:35]
	v_mfma_f32_16x16x32_bf16 v[20:23], v[170:173], v[202:205], v[20:23]
	v_mfma_f32_16x16x32_bf16 v[16:19], v[178:181], v[202:205], v[16:19]
	v_mfma_f32_16x16x32_bf16 v[4:7], v[170:173], v[210:213], v[4:7]
	v_mfma_f32_16x16x32_bf16 v[0:3], v[178:181], v[210:213], v[0:3]
	v_mfma_f32_16x16x32_bf16 v[52:55], v[174:177], v[190:193], v[52:55]
	v_mfma_f32_16x16x32_bf16 v[48:51], v[182:185], v[190:193], v[48:51]
	v_mfma_f32_16x16x32_bf16 v[36:39], v[174:177], v[198:201], v[36:39]
	v_mfma_f32_16x16x32_bf16 v[32:35], v[182:185], v[198:201], v[32:35]
	v_mfma_f32_16x16x32_bf16 v[20:23], v[174:177], v[206:209], v[20:23]
	v_mfma_f32_16x16x32_bf16 v[16:19], v[182:185], v[206:209], v[16:19]
	v_mfma_f32_16x16x32_bf16 v[4:7], v[174:177], v[214:217], v[4:7]
	v_mfma_f32_16x16x32_bf16 v[0:3], v[182:185], v[214:217], v[0:3]
	s_setprio 0
	s_barrier
	s_add_i32 s57, 0, 0x18000
	v_add_u32_e32 v165, s57, v148
	s_add_i32 s68, 0, 0x1c000
	ds_read_b128 v[152:155], v165
	ds_read_b128 v[156:159], v165 offset:1024
	ds_read_b128 v[160:163], v165 offset:2048
	ds_read_b128 v[166:169], v165 offset:3072
	v_add_u32_e32 v165, s68, v148
	ds_read_b128 v[170:173], v165
	ds_read_b128 v[174:177], v165 offset:1024
	ds_read_b128 v[178:181], v165 offset:2048
	ds_read_b128 v[182:185], v165 offset:3072
	s_add_u32 s50, s62, 0x40000
	s_addc_u32 s51, s63, 0
	s_mov_b32 m0, s35
	v_lshl_add_u64 v[226:227], s[50:51], 0, v[136:137]
	ds_read_b128 v[186:189], v151 offset:32768
	ds_read_b128 v[190:193], v151 offset:33792
	ds_read_b128 v[194:197], v151 offset:34816
	ds_read_b128 v[198:201], v151 offset:35840
	ds_read_b128 v[202:205], v151 offset:36864
	ds_read_b128 v[206:209], v151 offset:37888
	ds_read_b128 v[210:213], v151 offset:38912
	ds_read_b128 v[214:217], v151 offset:39936
	global_load_lds_dwordx4 v[226:227], off
	v_lshl_add_u64 v[226:227], s[50:51], 0, v[132:133]
	s_mov_b32 m0, s43
	s_nop 0
	global_load_lds_dwordx4 v[226:227], off
	s_waitcnt vmcnt(8)
	s_waitcnt lgkmcnt(0)
	s_barrier
	s_setprio 1
	v_mfma_f32_16x16x32_bf16 v[124:127], v[152:155], v[186:189], v[124:127]
	v_mfma_f32_16x16x32_bf16 v[120:123], v[160:163], v[186:189], v[120:123]
	v_mfma_f32_16x16x32_bf16 v[108:111], v[152:155], v[194:197], v[108:111]
	v_mfma_f32_16x16x32_bf16 v[104:107], v[160:163], v[194:197], v[104:107]
	v_mfma_f32_16x16x32_bf16 v[92:95], v[152:155], v[202:205], v[92:95]
	v_mfma_f32_16x16x32_bf16 v[88:91], v[160:163], v[202:205], v[88:91]
	v_mfma_f32_16x16x32_bf16 v[76:79], v[152:155], v[210:213], v[76:79]
	v_mfma_f32_16x16x32_bf16 v[72:75], v[160:163], v[210:213], v[72:75]
	v_mfma_f32_16x16x32_bf16 v[124:127], v[156:159], v[190:193], v[124:127]
	v_mfma_f32_16x16x32_bf16 v[120:123], v[166:169], v[190:193], v[120:123]
	v_mfma_f32_16x16x32_bf16 v[108:111], v[156:159], v[198:201], v[108:111]
	v_mfma_f32_16x16x32_bf16 v[104:107], v[166:169], v[198:201], v[104:107]
	v_mfma_f32_16x16x32_bf16 v[92:95], v[156:159], v[206:209], v[92:95]
	v_mfma_f32_16x16x32_bf16 v[88:91], v[166:169], v[206:209], v[88:91]
	v_mfma_f32_16x16x32_bf16 v[76:79], v[156:159], v[214:217], v[76:79]
	v_mfma_f32_16x16x32_bf16 v[72:75], v[166:169], v[214:217], v[72:75]
	v_mfma_f32_16x16x32_bf16 v[116:119], v[170:173], v[186:189], v[116:119]
	v_mfma_f32_16x16x32_bf16 v[112:115], v[178:181], v[186:189], v[112:115]
	v_mfma_f32_16x16x32_bf16 v[100:103], v[170:173], v[194:197], v[100:103]
	v_mfma_f32_16x16x32_bf16 v[96:99], v[178:181], v[194:197], v[96:99]
	v_mfma_f32_16x16x32_bf16 v[84:87], v[170:173], v[202:205], v[84:87]
	v_mfma_f32_16x16x32_bf16 v[80:83], v[178:181], v[202:205], v[80:83]
	v_mfma_f32_16x16x32_bf16 v[68:71], v[170:173], v[210:213], v[68:71]
	v_mfma_f32_16x16x32_bf16 v[64:67], v[178:181], v[210:213], v[64:67]
	v_mfma_f32_16x16x32_bf16 v[116:119], v[174:177], v[190:193], v[116:119]
	v_mfma_f32_16x16x32_bf16 v[112:115], v[182:185], v[190:193], v[112:115]
	v_mfma_f32_16x16x32_bf16 v[100:103], v[174:177], v[198:201], v[100:103]
	v_mfma_f32_16x16x32_bf16 v[96:99], v[182:185], v[198:201], v[96:99]
	v_mfma_f32_16x16x32_bf16 v[84:87], v[174:177], v[206:209], v[84:87]
	v_mfma_f32_16x16x32_bf16 v[80:83], v[182:185], v[206:209], v[80:83]
	v_mfma_f32_16x16x32_bf16 v[68:71], v[174:177], v[214:217], v[68:71]
	v_mfma_f32_16x16x32_bf16 v[64:67], v[182:185], v[214:217], v[64:67]
	s_setprio 0
	s_barrier
	s_add_i32 s50, s57, s3
	v_lshl_add_u64 v[218:219], v[218:219], 0, s[24:25]
	s_mov_b32 m0, s50
	ds_read_b128 v[186:189], v151 offset:49152
	ds_read_b128 v[190:193], v151 offset:50176
	ds_read_b128 v[194:197], v151 offset:51200
	ds_read_b128 v[198:201], v151 offset:52224
	ds_read_b128 v[202:205], v151 offset:53248
	ds_read_b128 v[206:209], v151 offset:54272
	ds_read_b128 v[210:213], v151 offset:55296
	ds_read_b128 v[214:217], v151 offset:56320
	global_load_lds_dwordx4 v[218:219], off
	s_add_i32 m0, s50, 0x2000
	s_add_u32 s50, s60, 0x40080
	v_lshl_add_u64 v[218:219], v[220:221], 0, s[24:25]
	s_addc_u32 s51, s61, 0
	s_add_i32 s57, s68, s3
	global_load_lds_dwordx4 v[218:219], off
	v_lshl_add_u64 v[218:219], s[50:51], 0, v[134:135]
	s_mov_b32 m0, s57
	s_nop 0
	global_load_lds_dwordx4 v[218:219], off
	v_lshl_add_u64 v[218:219], s[50:51], 0, v[130:131]
	s_add_i32 m0, s57, 0x2000
	s_nop 0
	global_load_lds_dwordx4 v[218:219], off
	v_lshl_add_u64 v[218:219], v[222:223], 0, s[24:25]
	s_mov_b32 m0, s44
	s_nop 0
	global_load_lds_dwordx4 v[218:219], off
	v_lshl_add_u64 v[218:219], v[224:225], 0, s[24:25]
	s_mov_b32 m0, s45
	s_nop 0
	global_load_lds_dwordx4 v[218:219], off
	s_waitcnt vmcnt(8)
	s_waitcnt lgkmcnt(0)
	s_barrier
	s_setprio 1
	v_mfma_f32_16x16x32_bf16 v[60:63], v[152:155], v[186:189], v[60:63]
	v_mfma_f32_16x16x32_bf16 v[56:59], v[160:163], v[186:189], v[56:59]
	v_mfma_f32_16x16x32_bf16 v[44:47], v[152:155], v[194:197], v[44:47]
	v_mfma_f32_16x16x32_bf16 v[40:43], v[160:163], v[194:197], v[40:43]
	v_mfma_f32_16x16x32_bf16 v[28:31], v[152:155], v[202:205], v[28:31]
	v_mfma_f32_16x16x32_bf16 v[24:27], v[160:163], v[202:205], v[24:27]
	v_mfma_f32_16x16x32_bf16 v[12:15], v[152:155], v[210:213], v[12:15]
	v_mfma_f32_16x16x32_bf16 v[8:11], v[160:163], v[210:213], v[8:11]
	v_mfma_f32_16x16x32_bf16 v[60:63], v[156:159], v[190:193], v[60:63]
	v_mfma_f32_16x16x32_bf16 v[56:59], v[166:169], v[190:193], v[56:59]
	v_mfma_f32_16x16x32_bf16 v[44:47], v[156:159], v[198:201], v[44:47]
	v_mfma_f32_16x16x32_bf16 v[40:43], v[166:169], v[198:201], v[40:43]
	v_mfma_f32_16x16x32_bf16 v[28:31], v[156:159], v[206:209], v[28:31]
	v_mfma_f32_16x16x32_bf16 v[24:27], v[166:169], v[206:209], v[24:27]
	v_mfma_f32_16x16x32_bf16 v[12:15], v[156:159], v[214:217], v[12:15]
	v_mfma_f32_16x16x32_bf16 v[8:11], v[166:169], v[214:217], v[8:11]
	v_mfma_f32_16x16x32_bf16 v[52:55], v[170:173], v[186:189], v[52:55]
	v_mfma_f32_16x16x32_bf16 v[48:51], v[178:181], v[186:189], v[48:51]
	v_mfma_f32_16x16x32_bf16 v[36:39], v[170:173], v[194:197], v[36:39]
	v_mfma_f32_16x16x32_bf16 v[32:35], v[178:181], v[194:197], v[32:35]
	v_mfma_f32_16x16x32_bf16 v[20:23], v[170:173], v[202:205], v[20:23]
	v_mfma_f32_16x16x32_bf16 v[16:19], v[178:181], v[202:205], v[16:19]
	v_mfma_f32_16x16x32_bf16 v[4:7], v[170:173], v[210:213], v[4:7]
	v_mfma_f32_16x16x32_bf16 v[0:3], v[178:181], v[210:213], v[0:3]
	v_mfma_f32_16x16x32_bf16 v[52:55], v[174:177], v[190:193], v[52:55]
	v_mfma_f32_16x16x32_bf16 v[48:51], v[182:185], v[190:193], v[48:51]
	v_mfma_f32_16x16x32_bf16 v[36:39], v[174:177], v[198:201], v[36:39]
	v_mfma_f32_16x16x32_bf16 v[32:35], v[182:185], v[198:201], v[32:35]
	v_mfma_f32_16x16x32_bf16 v[20:23], v[174:177], v[206:209], v[20:23]
	v_mfma_f32_16x16x32_bf16 v[16:19], v[182:185], v[206:209], v[16:19]
	v_mfma_f32_16x16x32_bf16 v[4:7], v[174:177], v[214:217], v[4:7]
	v_mfma_f32_16x16x32_bf16 v[0:3], v[182:185], v[214:217], v[0:3]
	s_add_i32 s49, s49, 2
	s_add_u32 s58, s58, 0x100
	s_addc_u32 s59, s59, 0
	s_add_u32 s42, s42, 0x100
	s_addc_u32 s48, s48, 0
	s_cmp_gt_u32 s49, 13
	s_setprio 0
	s_barrier
	s_cbranch_scc0 .LBB0_1658
	s_and_b64 vcc, exec, s[26:27]
	s_cbranch_vccz .LBB0_1661
	s_barrier

.LBB0_1735:
	ds_read_b128 v[162:165], v159
	ds_read_b128 v[166:169], v159 offset:1024
	ds_read_b128 v[170:173], v159 offset:2048
	ds_read_b128 v[174:177], v159 offset:3072
	ds_read_b128 v[178:181], v160
	ds_read_b128 v[182:185], v160 offset:1024
	ds_read_b128 v[186:189], v160 offset:2048
	ds_read_b128 v[190:193], v160 offset:3072
	s_add_i32 s68, s56, 2
	s_add_u32 s54, s52, 0x100
	s_addc_u32 s55, s53, 0
	s_cmp_eq_u32 s34, s56
	s_cselect_b32 s56, s48, s37
	s_cselect_b32 s59, s39, s55
	s_cselect_b32 s58, s38, s54
	s_cselect_b32 s57, s49, s42
	v_lshl_add_u64 v[146:147], s[52:53], 0, v[142:143]
	s_add_i32 m0, s18, 0xc000
	ds_read_b128 v[194:197], v161
	ds_read_b128 v[198:201], v161 offset:1024
	ds_read_b128 v[202:205], v161 offset:2048
	ds_read_b128 v[206:209], v161 offset:3072
	ds_read_b128 v[210:213], v161 offset:4096
	ds_read_b128 v[214:217], v161 offset:5120
	ds_read_b128 v[218:221], v161 offset:6144
	ds_read_b128 v[222:225], v161 offset:7168
	global_load_lds_dwordx4 v[146:147], off
	v_lshl_add_u64 v[146:147], s[52:53], 0, v[144:145]
	s_add_i32 m0, s18, 0xe000
	s_nop 0
	global_load_lds_dwordx4 v[146:147], off
	s_waitcnt vmcnt(8)
	s_waitcnt lgkmcnt(0)
	s_barrier
	s_setprio 1
	v_mfma_f32_16x16x32_bf16 v[124:127], v[162:165], v[194:197], v[124:127]
	v_mfma_f32_16x16x32_bf16 v[120:123], v[170:173], v[194:197], v[120:123]
	v_mfma_f32_16x16x32_bf16 v[108:111], v[162:165], v[202:205], v[108:111]
	v_mfma_f32_16x16x32_bf16 v[104:107], v[170:173], v[202:205], v[104:107]
	v_mfma_f32_16x16x32_bf16 v[92:95], v[162:165], v[210:213], v[92:95]
	v_mfma_f32_16x16x32_bf16 v[88:91], v[170:173], v[210:213], v[88:91]
	v_mfma_f32_16x16x32_bf16 v[76:79], v[162:165], v[218:221], v[76:79]
	v_mfma_f32_16x16x32_bf16 v[72:75], v[170:173], v[218:221], v[72:75]
	v_mfma_f32_16x16x32_bf16 v[124:127], v[166:169], v[198:201], v[124:127]
	v_mfma_f32_16x16x32_bf16 v[120:123], v[174:177], v[198:201], v[120:123]
	v_mfma_f32_16x16x32_bf16 v[108:111], v[166:169], v[206:209], v[108:111]
	v_mfma_f32_16x16x32_bf16 v[104:107], v[174:177], v[206:209], v[104:107]
	v_mfma_f32_16x16x32_bf16 v[92:95], v[166:169], v[214:217], v[92:95]
	v_mfma_f32_16x16x32_bf16 v[88:91], v[174:177], v[214:217], v[88:91]
	v_mfma_f32_16x16x32_bf16 v[76:79], v[166:169], v[222:225], v[76:79]
	v_mfma_f32_16x16x32_bf16 v[72:75], v[174:177], v[222:225], v[72:75]
	v_mfma_f32_16x16x32_bf16 v[116:119], v[178:181], v[194:197], v[116:119]
	v_mfma_f32_16x16x32_bf16 v[112:115], v[186:189], v[194:197], v[112:115]
	v_mfma_f32_16x16x32_bf16 v[100:103], v[178:181], v[202:205], v[100:103]
	v_mfma_f32_16x16x32_bf16 v[96:99], v[186:189], v[202:205], v[96:99]
	v_mfma_f32_16x16x32_bf16 v[84:87], v[178:181], v[210:213], v[84:87]
	v_mfma_f32_16x16x32_bf16 v[80:83], v[186:189], v[210:213], v[80:83]
	v_mfma_f32_16x16x32_bf16 v[68:71], v[178:181], v[218:221], v[68:71]
	v_mfma_f32_16x16x32_bf16 v[64:67], v[186:189], v[218:221], v[64:67]
	v_mfma_f32_16x16x32_bf16 v[116:119], v[182:185], v[198:201], v[116:119]
	v_mfma_f32_16x16x32_bf16 v[112:115], v[190:193], v[198:201], v[112:115]
	v_mfma_f32_16x16x32_bf16 v[100:103], v[182:185], v[206:209], v[100:103]
	v_mfma_f32_16x16x32_bf16 v[96:99], v[190:193], v[206:209], v[96:99]
	v_mfma_f32_16x16x32_bf16 v[84:87], v[182:185], v[214:217], v[84:87]
	v_mfma_f32_16x16x32_bf16 v[80:83], v[190:193], v[214:217], v[80:83]
	v_mfma_f32_16x16x32_bf16 v[68:71], v[182:185], v[222:225], v[68:71]
	v_mfma_f32_16x16x32_bf16 v[64:67], v[190:193], v[222:225], v[64:67]
	s_setprio 0
	s_barrier
	s_add_i32 s52, s63, s15
	v_lshl_add_u64 v[146:147], s[56:57], 0, v[132:133]
	s_mov_b32 m0, s52
	ds_read_b128 v[194:197], v161 offset:16384
	ds_read_b128 v[198:201], v161 offset:17408
	ds_read_b128 v[202:205], v161 offset:18432
	ds_read_b128 v[206:209], v161 offset:19456
	ds_read_b128 v[210:213], v161 offset:20480
	ds_read_b128 v[214:217], v161 offset:21504
	ds_read_b128 v[218:221], v161 offset:22528
	ds_read_b128 v[222:225], v161 offset:23552
	global_load_lds_dwordx4 v[146:147], off
	s_add_i32 m0, s52, 0x2000
	s_add_u32 s52, s56, 0xb0000
	v_lshl_add_u64 v[226:227], s[56:57], 0, v[136:137]
	s_addc_u32 s53, s57, 0
	s_add_i32 s69, s64, s15
	global_load_lds_dwordx4 v[226:227], off
	v_lshl_add_u64 v[228:229], s[52:53], 0, v[132:133]
	s_mov_b32 m0, s69
	v_lshl_add_u64 v[230:231], s[58:59], 0, v[134:135]
	global_load_lds_dwordx4 v[228:229], off
	v_lshl_add_u64 v[228:229], s[52:53], 0, v[136:137]
	s_add_i32 m0, s69, 0x2000
	s_nop 0
	global_load_lds_dwordx4 v[228:229], off
	v_lshl_add_u64 v[228:229], s[58:59], 0, v[130:131]
	s_mov_b32 m0, s18
	s_nop 0
	global_load_lds_dwordx4 v[228:229], off
	s_mov_b32 m0, s19
	s_nop 0
	global_load_lds_dwordx4 v[230:231], off
	s_waitcnt vmcnt(8)
	s_waitcnt lgkmcnt(0)
	s_barrier
	s_setprio 1
	v_mfma_f32_16x16x32_bf16 v[60:63], v[162:165], v[194:197], v[60:63]
	v_mfma_f32_16x16x32_bf16 v[56:59], v[170:173], v[194:197], v[56:59]
	v_mfma_f32_16x16x32_bf16 v[44:47], v[162:165], v[202:205], v[44:47]
	v_mfma_f32_16x16x32_bf16 v[40:43], v[170:173], v[202:205], v[40:43]
	v_mfma_f32_16x16x32_bf16 v[28:31], v[162:165], v[210:213], v[28:31]
	v_mfma_f32_16x16x32_bf16 v[24:27], v[170:173], v[210:213], v[24:27]
	v_mfma_f32_16x16x32_bf16 v[12:15], v[162:165], v[218:221], v[12:15]
	v_mfma_f32_16x16x32_bf16 v[8:11], v[170:173], v[218:221], v[8:11]
	v_mfma_f32_16x16x32_bf16 v[60:63], v[166:169], v[198:201], v[60:63]
	v_mfma_f32_16x16x32_bf16 v[56:59], v[174:177], v[198:201], v[56:59]
	v_mfma_f32_16x16x32_bf16 v[44:47], v[166:169], v[206:209], v[44:47]
	v_mfma_f32_16x16x32_bf16 v[40:43], v[174:177], v[206:209], v[40:43]
	v_mfma_f32_16x16x32_bf16 v[28:31], v[166:169], v[214:217], v[28:31]
	v_mfma_f32_16x16x32_bf16 v[24:27], v[174:177], v[214:217], v[24:27]
	v_mfma_f32_16x16x32_bf16 v[12:15], v[166:169], v[222:225], v[12:15]
	v_mfma_f32_16x16x32_bf16 v[8:11], v[174:177], v[222:225], v[8:11]
	v_mfma_f32_16x16x32_bf16 v[52:55], v[178:181], v[194:197], v[52:55]
	v_mfma_f32_16x16x32_bf16 v[48:51], v[186:189], v[194:197], v[48:51]
	v_mfma_f32_16x16x32_bf16 v[36:39], v[178:181], v[202:205], v[36:39]
	v_mfma_f32_16x16x32_bf16 v[32:35], v[186:189], v[202:205], v[32:35]
	v_mfma_f32_16x16x32_bf16 v[20:23], v[178:181], v[210:213], v[20:23]
	v_mfma_f32_16x16x32_bf16 v[16:19], v[186:189], v[210:213], v[16:19]
	v_mfma_f32_16x16x32_bf16 v[4:7], v[178:181], v[218:221], v[4:7]
	v_mfma_f32_16x16x32_bf16 v[0:3], v[186:189], v[218:221], v[0:3]
	v_mfma_f32_16x16x32_bf16 v[52:55], v[182:185], v[198:201], v[52:55]
	v_mfma_f32_16x16x32_bf16 v[48:51], v[190:193], v[198:201], v[48:51]
	v_mfma_f32_16x16x32_bf16 v[36:39], v[182:185], v[206:209], v[36:39]
	v_mfma_f32_16x16x32_bf16 v[32:35], v[190:193], v[206:209], v[32:35]
	v_mfma_f32_16x16x32_bf16 v[20:23], v[182:185], v[214:217], v[20:23]
	v_mfma_f32_16x16x32_bf16 v[16:19], v[190:193], v[214:217], v[16:19]
	v_mfma_f32_16x16x32_bf16 v[4:7], v[182:185], v[222:225], v[4:7]
	v_mfma_f32_16x16x32_bf16 v[0:3], v[190:193], v[222:225], v[0:3]
	s_setprio 0
	s_barrier
	s_add_i32 s69, 0, 0x18000
	v_add_u32_e32 v138, s69, v141
	s_add_i32 s70, 0, 0x1c000
	ds_read_b128 v[162:165], v138
	ds_read_b128 v[166:169], v138 offset:1024
	ds_read_b128 v[170:173], v138 offset:2048
	ds_read_b128 v[174:177], v138 offset:3072
	v_add_u32_e32 v138, s70, v141
	ds_read_b128 v[178:181], v138
	ds_read_b128 v[182:185], v138 offset:1024
	ds_read_b128 v[186:189], v138 offset:2048
	ds_read_b128 v[190:193], v138 offset:3072
	s_add_u32 s52, s58, 0xb0000
	s_addc_u32 s53, s59, 0
	s_mov_b32 m0, s35
	v_lshl_add_u64 v[232:233], s[52:53], 0, v[130:131]
	ds_read_b128 v[194:197], v161 offset:32768
	ds_read_b128 v[198:201], v161 offset:33792
	ds_read_b128 v[202:205], v161 offset:34816
	ds_read_b128 v[206:209], v161 offset:35840
	ds_read_b128 v[210:213], v161 offset:36864
	ds_read_b128 v[214:217], v161 offset:37888
	ds_read_b128 v[218:221], v161 offset:38912
	ds_read_b128 v[222:225], v161 offset:39936
	global_load_lds_dwordx4 v[232:233], off
	v_lshl_add_u64 v[232:233], s[52:53], 0, v[134:135]
	s_mov_b32 m0, s43
	s_nop 0
	global_load_lds_dwordx4 v[232:233], off
	s_waitcnt vmcnt(8)
	s_waitcnt lgkmcnt(0)
	s_barrier
	s_setprio 1
	v_mfma_f32_16x16x32_bf16 v[124:127], v[162:165], v[194:197], v[124:127]
	v_mfma_f32_16x16x32_bf16 v[120:123], v[170:173], v[194:197], v[120:123]
	v_mfma_f32_16x16x32_bf16 v[108:111], v[162:165], v[202:205], v[108:111]
	v_mfma_f32_16x16x32_bf16 v[104:107], v[170:173], v[202:205], v[104:107]
	v_mfma_f32_16x16x32_bf16 v[92:95], v[162:165], v[210:213], v[92:95]
	v_mfma_f32_16x16x32_bf16 v[88:91], v[170:173], v[210:213], v[88:91]
	v_mfma_f32_16x16x32_bf16 v[76:79], v[162:165], v[218:221], v[76:79]
	v_mfma_f32_16x16x32_bf16 v[72:75], v[170:173], v[218:221], v[72:75]
	v_mfma_f32_16x16x32_bf16 v[124:127], v[166:169], v[198:201], v[124:127]
	v_mfma_f32_16x16x32_bf16 v[120:123], v[174:177], v[198:201], v[120:123]
	v_mfma_f32_16x16x32_bf16 v[108:111], v[166:169], v[206:209], v[108:111]
	v_mfma_f32_16x16x32_bf16 v[104:107], v[174:177], v[206:209], v[104:107]
	v_mfma_f32_16x16x32_bf16 v[92:95], v[166:169], v[214:217], v[92:95]
	v_mfma_f32_16x16x32_bf16 v[88:91], v[174:177], v[214:217], v[88:91]
	v_mfma_f32_16x16x32_bf16 v[76:79], v[166:169], v[222:225], v[76:79]
	v_mfma_f32_16x16x32_bf16 v[72:75], v[174:177], v[222:225], v[72:75]
	v_mfma_f32_16x16x32_bf16 v[116:119], v[178:181], v[194:197], v[116:119]
	v_mfma_f32_16x16x32_bf16 v[112:115], v[186:189], v[194:197], v[112:115]
	v_mfma_f32_16x16x32_bf16 v[100:103], v[178:181], v[202:205], v[100:103]
	v_mfma_f32_16x16x32_bf16 v[96:99], v[186:189], v[202:205], v[96:99]
	v_mfma_f32_16x16x32_bf16 v[84:87], v[178:181], v[210:213], v[84:87]
	v_mfma_f32_16x16x32_bf16 v[80:83], v[186:189], v[210:213], v[80:83]
	v_mfma_f32_16x16x32_bf16 v[68:71], v[178:181], v[218:221], v[68:71]
	v_mfma_f32_16x16x32_bf16 v[64:67], v[186:189], v[218:221], v[64:67]
	v_mfma_f32_16x16x32_bf16 v[116:119], v[182:185], v[198:201], v[116:119]
	v_mfma_f32_16x16x32_bf16 v[112:115], v[190:193], v[198:201], v[112:115]
	v_mfma_f32_16x16x32_bf16 v[100:103], v[182:185], v[206:209], v[100:103]
	v_mfma_f32_16x16x32_bf16 v[96:99], v[190:193], v[206:209], v[96:99]
	v_mfma_f32_16x16x32_bf16 v[84:87], v[182:185], v[214:217], v[84:87]
	v_mfma_f32_16x16x32_bf16 v[80:83], v[190:193], v[214:217], v[80:83]
	v_mfma_f32_16x16x32_bf16 v[68:71], v[182:185], v[222:225], v[68:71]
	v_mfma_f32_16x16x32_bf16 v[64:67], v[190:193], v[222:225], v[64:67]
	s_setprio 0
	s_barrier
	s_add_i32 s52, s69, s15
	v_lshl_add_u64 v[146:147], v[146:147], 0, s[22:23]
	s_mov_b32 m0, s52
	ds_read_b128 v[194:197], v161 offset:49152
	ds_read_b128 v[198:201], v161 offset:50176
	ds_read_b128 v[202:205], v161 offset:51200
	ds_read_b128 v[206:209], v161 offset:52224
	ds_read_b128 v[210:213], v161 offset:53248
	ds_read_b128 v[214:217], v161 offset:54272
	ds_read_b128 v[218:221], v161 offset:55296
	ds_read_b128 v[222:225], v161 offset:56320
	global_load_lds_dwordx4 v[146:147], off
	s_add_i32 m0, s52, 0x2000
	s_add_u32 s52, s56, 0xb0080
	v_lshl_add_u64 v[146:147], v[226:227], 0, s[22:23]
	s_addc_u32 s53, s57, 0
	s_add_i32 s56, s70, s15
	global_load_lds_dwordx4 v[146:147], off
	v_lshl_add_u64 v[146:147], s[52:53], 0, v[132:133]
	s_mov_b32 m0, s56
	s_nop 0
	global_load_lds_dwordx4 v[146:147], off
	v_lshl_add_u64 v[146:147], s[52:53], 0, v[136:137]
	s_add_i32 m0, s56, 0x2000
	s_nop 0
	global_load_lds_dwordx4 v[146:147], off
	v_lshl_add_u64 v[146:147], v[228:229], 0, s[22:23]
	s_mov_b32 m0, s46
	s_nop 0
	global_load_lds_dwordx4 v[146:147], off
	v_lshl_add_u64 v[146:147], v[230:231], 0, s[22:23]
	s_mov_b32 m0, s47
	s_nop 0
	global_load_lds_dwordx4 v[146:147], off
	s_waitcnt vmcnt(8)
	s_waitcnt lgkmcnt(0)
	s_barrier
	s_setprio 1
	v_mfma_f32_16x16x32_bf16 v[60:63], v[162:165], v[194:197], v[60:63]
	v_mfma_f32_16x16x32_bf16 v[56:59], v[170:173], v[194:197], v[56:59]
	v_mfma_f32_16x16x32_bf16 v[44:47], v[162:165], v[202:205], v[44:47]
	v_mfma_f32_16x16x32_bf16 v[40:43], v[170:173], v[202:205], v[40:43]
	v_mfma_f32_16x16x32_bf16 v[28:31], v[162:165], v[210:213], v[28:31]
	v_mfma_f32_16x16x32_bf16 v[24:27], v[170:173], v[210:213], v[24:27]
	v_mfma_f32_16x16x32_bf16 v[12:15], v[162:165], v[218:221], v[12:15]
	v_mfma_f32_16x16x32_bf16 v[8:11], v[170:173], v[218:221], v[8:11]
	v_mfma_f32_16x16x32_bf16 v[60:63], v[166:169], v[198:201], v[60:63]
	v_mfma_f32_16x16x32_bf16 v[56:59], v[174:177], v[198:201], v[56:59]
	v_mfma_f32_16x16x32_bf16 v[44:47], v[166:169], v[206:209], v[44:47]
	v_mfma_f32_16x16x32_bf16 v[40:43], v[174:177], v[206:209], v[40:43]
	v_mfma_f32_16x16x32_bf16 v[28:31], v[166:169], v[214:217], v[28:31]
	v_mfma_f32_16x16x32_bf16 v[24:27], v[174:177], v[214:217], v[24:27]
	v_mfma_f32_16x16x32_bf16 v[12:15], v[166:169], v[222:225], v[12:15]
	v_mfma_f32_16x16x32_bf16 v[8:11], v[174:177], v[222:225], v[8:11]
	v_mfma_f32_16x16x32_bf16 v[52:55], v[178:181], v[194:197], v[52:55]
	v_mfma_f32_16x16x32_bf16 v[48:51], v[186:189], v[194:197], v[48:51]
	v_mfma_f32_16x16x32_bf16 v[36:39], v[178:181], v[202:205], v[36:39]
	v_mfma_f32_16x16x32_bf16 v[32:35], v[186:189], v[202:205], v[32:35]
	v_mfma_f32_16x16x32_bf16 v[20:23], v[178:181], v[210:213], v[20:23]
	v_mfma_f32_16x16x32_bf16 v[16:19], v[186:189], v[210:213], v[16:19]
	v_mfma_f32_16x16x32_bf16 v[4:7], v[178:181], v[218:221], v[4:7]
	v_mfma_f32_16x16x32_bf16 v[0:3], v[186:189], v[218:221], v[0:3]
	v_mfma_f32_16x16x32_bf16 v[52:55], v[182:185], v[198:201], v[52:55]
	v_mfma_f32_16x16x32_bf16 v[48:51], v[190:193], v[198:201], v[48:51]
	v_mfma_f32_16x16x32_bf16 v[36:39], v[182:185], v[206:209], v[36:39]
	v_mfma_f32_16x16x32_bf16 v[32:35], v[190:193], v[206:209], v[32:35]
	v_mfma_f32_16x16x32_bf16 v[20:23], v[182:185], v[214:217], v[20:23]
	v_mfma_f32_16x16x32_bf16 v[16:19], v[190:193], v[214:217], v[16:19]
	v_mfma_f32_16x16x32_bf16 v[4:7], v[182:185], v[222:225], v[4:7]
	v_mfma_f32_16x16x32_bf16 v[0:3], v[190:193], v[222:225], v[0:3]
	s_add_u32 s37, s37, 0x100
	s_addc_u32 s42, s42, 0
	s_cmp_ge_u32 s68, s33
	s_mov_b64 s[52:53], s[54:55]
	s_mov_b32 s56, s68
	s_setprio 0
	s_barrier
	s_cbranch_scc0 .LBB0_1735
	s_xor_b64 s[50:51], s[50:51], -1
	s_and_b64 vcc, exec, s[24:25]
	s_cbranch_vccz .LBB0_1757
